# v53 plus R loop edge rotated: toggles, counter and exit test moved in front of the interval-end barrier
# speedup vs baseline: 1.0126x; 1.0076x over previous
; #define LAS __attribute__((address_space(3)))
; template <int CTRL> __device__ __forceinline__ float dppf(float v) { return __builtin_bit_cast(float, __builtin_amdgcn_update_dpp(0, __builtin_bit_cast(int, v), CTRL, 0xF, 0xF, true)); }
; #define LO2(v) __builtin_shufflevector(v, v, 0, 1)
; #define HI2(v) __builtin_shufflevector(v, v, 2, 3)
; __device__ __forceinline__ void phase_scan(const Args& a, LAS unsigned char* lds) {
;     ...
;                 for (int s = 0; s < TC; ++s) {
;                     const LAS float* o = obase + (s + 1) * 320;
;                     const f32x4 now = *(const LAS f32x4*)(o), noa = *(const LAS f32x4*)(o + 4), nob = *(const LAS f32x4*)(o + 8), nok = *(const LAS f32x4*)(o + 12), norr = *(const LAS f32x4*)(o + 16);
;                     const f32x2 nvv = *(const LAS f32x2*)(vbase + (s + 1) * 64);
;                     const f32x2 p = pkfma_b<1>(C3, HI2(oa), pkfma_b<0>(C2, HI2(oa), pkfma_b<1>(C1, LO2(oa), pkmul_b<0>(C0, LO2(oa)))));
;                     float sa0 = p.x, sa1 = p.y;
;                     sa0 = reduce16(sa0); asm volatile("" : "+v"(sa0)); sa1 = reduce16(sa1);
;                     const f32x2 sap = {sa0, sa1};
;                     C0 = pkfma_b<0>(vv, LO2(ok), pkfma_b<0>(sap, LO2(ob), pkmul_b<0>(C0, LO2(ow))));
;                     C1 = pkfma_b<1>(vv, LO2(ok), pkfma_b<1>(sap, LO2(ob), pkmul_b<1>(C1, LO2(ow))));
;                     C2 = pkfma_b<0>(vv, HI2(ok), pkfma_b<0>(sap, HI2(ob), pkmul_b<0>(C2, HI2(ow))));
;                     C3 = pkfma_b<1>(vv, HI2(ok), pkfma_b<1>(sap, HI2(ob), pkmul_b<1>(C3, HI2(ow))));
;                     const f32x2 q = pkfma_b<1>(C3, HI2(orr), pkfma_b<0>(C2, HI2(orr), pkfma_b<1>(C1, LO2(orr), pkmul_b<0>(C0, LO2(orr)))));
;                     float y0 = q.x, y1 = q.y;
;                     y0 += dppf<0xB1>(y0); y1 += dppf<0xB1>(y1);
;                     *(LAS f32x2*)(yb + ((s * 32 + (r0 >> 1)) * 8 + ((lane >> 1) & 7)) * 2) = (f32x2){y0, y1};
;                     ow = now; oa = noa; ob = nob; ok = nok; orr = norr; vv = nvv;
;                 }
.LW_rloop:
	s_waitcnt lgkmcnt(10)
	v_pk_mul_f32 v[168:169], v[236:237], v[100:101] op_sel_hi:[1,0]
	v_pk_mul_f32 v[170:171], v[238:239], v[100:101] op_sel:[0,1]
	v_pk_fma_f32 v[168:169], v[240:241], v[102:103], v[168:169] op_sel_hi:[1,0,1]
	v_pk_fma_f32 v[170:171], v[242:243], v[102:103], v[170:171] op_sel:[0,1,0]
	v_pk_fma_f32 v[168:169], v[244:245], v[104:105], v[168:169] op_sel_hi:[1,0,1]
	v_pk_fma_f32 v[170:171], v[246:247], v[104:105], v[170:171] op_sel:[0,1,0]
	v_pk_fma_f32 v[168:169], v[248:249], v[106:107], v[168:169] op_sel_hi:[1,0,1]
	v_pk_fma_f32 v[170:171], v[250:251], v[106:107], v[170:171] op_sel:[0,1,0]
	ds_read_b128 v[100:103], v252 offset:1296
	ds_read_b128 v[104:107], v252 offset:1376
	v_pk_add_f32 v[168:169], v[168:169], v[170:171]
	s_waitcnt lgkmcnt(10)
	v_pk_mul_f32 v[236:237], v[236:237], v[108:109] op_sel_hi:[1,0]
	v_pk_mul_f32 v[238:239], v[238:239], v[108:109] op_sel:[0,1]
	v_pk_mul_f32 v[240:241], v[240:241], v[110:111] op_sel_hi:[1,0]
	v_pk_mul_f32 v[242:243], v[242:243], v[110:111] op_sel:[0,1]
	v_pk_mul_f32 v[244:245], v[244:245], v[112:113] op_sel_hi:[1,0]
	v_pk_mul_f32 v[246:247], v[246:247], v[112:113] op_sel:[0,1]
	v_pk_mul_f32 v[248:249], v[248:249], v[114:115] op_sel_hi:[1,0]
	v_pk_mul_f32 v[250:251], v[250:251], v[114:115] op_sel:[0,1]
	v_add_f32_dpp v168, v168, v168 quad_perm:[1,0,3,2] row_mask:0xf bank_mask:0xf bound_ctrl:1
	v_add_f32_dpp v169, v169, v169 quad_perm:[1,0,3,2] row_mask:0xf bank_mask:0xf bound_ctrl:1
	ds_read_b128 v[108:111], v252 offset:1280
	v_add_f32_dpp v168, v168, v168 quad_perm:[2,3,0,1] row_mask:0xf bank_mask:0xf bound_ctrl:1
	v_add_f32_dpp v169, v169, v169 quad_perm:[2,3,0,1] row_mask:0xf bank_mask:0xf bound_ctrl:1
	ds_read_b128 v[112:115], v252 offset:1360
	v_add_f32_dpp v168, v168, v168 row_half_mirror row_mask:0xf bank_mask:0xf bound_ctrl:1
	v_add_f32_dpp v169, v169, v169 row_half_mirror row_mask:0xf bank_mask:0xf bound_ctrl:1
	s_waitcnt lgkmcnt(10)
	v_pk_fma_f32 v[236:237], v[168:169], v[116:117], v[236:237] op_sel_hi:[1,0,1]
	v_pk_fma_f32 v[238:239], v[168:169], v[116:117], v[238:239] op_sel:[0,1,0]
	v_pk_fma_f32 v[240:241], v[168:169], v[118:119], v[240:241] op_sel_hi:[1,0,1]
	v_pk_fma_f32 v[242:243], v[168:169], v[118:119], v[242:243] op_sel:[0,1,0]
	v_pk_fma_f32 v[244:245], v[168:169], v[120:121], v[244:245] op_sel_hi:[1,0,1]
	v_pk_fma_f32 v[246:247], v[168:169], v[120:121], v[246:247] op_sel:[0,1,0]
	v_pk_fma_f32 v[248:249], v[168:169], v[122:123], v[248:249] op_sel_hi:[1,0,1]
	v_pk_fma_f32 v[250:251], v[168:169], v[122:123], v[250:251] op_sel:[0,1,0]
	ds_read_b128 v[116:119], v252 offset:1312
	ds_read_b128 v[120:123], v252 offset:1392
	s_waitcnt lgkmcnt(9)
	v_pk_fma_f32 v[236:237], v[166:167], v[124:125], v[236:237] op_sel_hi:[1,0,1]
	v_pk_fma_f32 v[238:239], v[166:167], v[124:125], v[238:239] op_sel:[0,1,0]
	v_pk_fma_f32 v[240:241], v[166:167], v[126:127], v[240:241] op_sel_hi:[1,0,1]
	v_pk_fma_f32 v[242:243], v[166:167], v[126:127], v[242:243] op_sel:[0,1,0]
	v_pk_fma_f32 v[244:245], v[166:167], v[128:129], v[244:245] op_sel_hi:[1,0,1]
	v_pk_fma_f32 v[246:247], v[166:167], v[128:129], v[246:247] op_sel:[0,1,0]
	v_pk_fma_f32 v[248:249], v[166:167], v[130:131], v[248:249] op_sel_hi:[1,0,1]
	v_pk_fma_f32 v[250:251], v[166:167], v[130:131], v[250:251] op_sel:[0,1,0]
	ds_read_b128 v[124:127], v252 offset:1328
	ds_read_b128 v[128:131], v252 offset:1408
	ds_read_b64 v[166:167], v253 offset:256
	s_waitcnt lgkmcnt(10)
	v_pk_mul_f32 v[172:173], v[236:237], v[132:133] op_sel_hi:[1,0]
	v_pk_mul_f32 v[174:175], v[238:239], v[132:133] op_sel:[0,1]
	v_pk_fma_f32 v[172:173], v[240:241], v[134:135], v[172:173] op_sel_hi:[1,0,1]
	v_pk_fma_f32 v[174:175], v[242:243], v[134:135], v[174:175] op_sel:[0,1,0]
	v_pk_fma_f32 v[172:173], v[244:245], v[136:137], v[172:173] op_sel_hi:[1,0,1]
	v_pk_fma_f32 v[174:175], v[246:247], v[136:137], v[174:175] op_sel:[0,1,0]
	v_pk_fma_f32 v[172:173], v[248:249], v[138:139], v[172:173] op_sel_hi:[1,0,1]
	v_pk_fma_f32 v[174:175], v[250:251], v[138:139], v[174:175] op_sel:[0,1,0]
	ds_read_b128 v[132:135], v252 offset:1344
	ds_read_b128 v[136:139], v252 offset:1424
	v_pk_add_f32 v[172:173], v[172:173], v[174:175]
	ds_write_b64 v254, v[172:173]
	s_waitcnt lgkmcnt(10)
	v_pk_mul_f32 v[168:169], v[236:237], v[100:101] op_sel_hi:[1,0]
	v_pk_mul_f32 v[170:171], v[238:239], v[100:101] op_sel:[0,1]
	v_pk_fma_f32 v[168:169], v[240:241], v[102:103], v[168:169] op_sel_hi:[1,0,1]
	v_pk_fma_f32 v[170:171], v[242:243], v[102:103], v[170:171] op_sel:[0,1,0]
	v_pk_fma_f32 v[168:169], v[244:245], v[104:105], v[168:169] op_sel_hi:[1,0,1]
	v_pk_fma_f32 v[170:171], v[246:247], v[104:105], v[170:171] op_sel:[0,1,0]
	v_pk_fma_f32 v[168:169], v[248:249], v[106:107], v[168:169] op_sel_hi:[1,0,1]
	v_pk_fma_f32 v[170:171], v[250:251], v[106:107], v[170:171] op_sel:[0,1,0]
	ds_read_b128 v[100:103], v252 offset:2576
	ds_read_b128 v[104:107], v252 offset:2656
	v_pk_add_f32 v[168:169], v[168:169], v[170:171]
	s_waitcnt lgkmcnt(10)
	v_pk_mul_f32 v[236:237], v[236:237], v[108:109] op_sel_hi:[1,0]
	v_pk_mul_f32 v[238:239], v[238:239], v[108:109] op_sel:[0,1]
	v_pk_mul_f32 v[240:241], v[240:241], v[110:111] op_sel_hi:[1,0]
	v_pk_mul_f32 v[242:243], v[242:243], v[110:111] op_sel:[0,1]
	v_pk_mul_f32 v[244:245], v[244:245], v[112:113] op_sel_hi:[1,0]
	v_pk_mul_f32 v[246:247], v[246:247], v[112:113] op_sel:[0,1]
	v_pk_mul_f32 v[248:249], v[248:249], v[114:115] op_sel_hi:[1,0]
	v_pk_mul_f32 v[250:251], v[250:251], v[114:115] op_sel:[0,1]
	v_add_f32_dpp v168, v168, v168 quad_perm:[1,0,3,2] row_mask:0xf bank_mask:0xf bound_ctrl:1
	v_add_f32_dpp v169, v169, v169 quad_perm:[1,0,3,2] row_mask:0xf bank_mask:0xf bound_ctrl:1
	ds_read_b128 v[108:111], v252 offset:2560
	v_add_f32_dpp v168, v168, v168 quad_perm:[2,3,0,1] row_mask:0xf bank_mask:0xf bound_ctrl:1
	v_add_f32_dpp v169, v169, v169 quad_perm:[2,3,0,1] row_mask:0xf bank_mask:0xf bound_ctrl:1
	ds_read_b128 v[112:115], v252 offset:2640
	v_add_f32_dpp v168, v168, v168 row_half_mirror row_mask:0xf bank_mask:0xf bound_ctrl:1
	v_add_f32_dpp v169, v169, v169 row_half_mirror row_mask:0xf bank_mask:0xf bound_ctrl:1
	s_waitcnt lgkmcnt(10)
; #define LAS __attribute__((address_space(3)))
; template <int CTRL> __device__ __forceinline__ float dppf(float v) { return __builtin_bit_cast(float, __builtin_amdgcn_update_dpp(0, __builtin_bit_cast(int, v), CTRL, 0xF, 0xF, true)); }
; #define LO2(v) __builtin_shufflevector(v, v, 0, 1)
; #define HI2(v) __builtin_shufflevector(v, v, 2, 3)
; __device__ __forceinline__ void phase_scan(const Args& a, LAS unsigned char* lds) {
;     ...
;                 for (int s = 0; s < TC; ++s) {
;                     const LAS float* o = obase + (s + 1) * 320;
;                     const f32x4 now = *(const LAS f32x4*)(o), noa = *(const LAS f32x4*)(o + 4), nob = *(const LAS f32x4*)(o + 8), nok = *(const LAS f32x4*)(o + 12), norr = *(const LAS f32x4*)(o + 16);
;                     const f32x2 nvv = *(const LAS f32x2*)(vbase + (s + 1) * 64);
;                     const f32x2 p = pkfma_b<1>(C3, HI2(oa), pkfma_b<0>(C2, HI2(oa), pkfma_b<1>(C1, LO2(oa), pkmul_b<0>(C0, LO2(oa)))));
;                     float sa0 = p.x, sa1 = p.y;
;                     sa0 = reduce16(sa0); asm volatile("" : "+v"(sa0)); sa1 = reduce16(sa1);
;                     const f32x2 sap = {sa0, sa1};
;                     C0 = pkfma_b<0>(vv, LO2(ok), pkfma_b<0>(sap, LO2(ob), pkmul_b<0>(C0, LO2(ow))));
;                     C1 = pkfma_b<1>(vv, LO2(ok), pkfma_b<1>(sap, LO2(ob), pkmul_b<1>(C1, LO2(ow))));
;                     C2 = pkfma_b<0>(vv, HI2(ok), pkfma_b<0>(sap, HI2(ob), pkmul_b<0>(C2, HI2(ow))));
;                     C3 = pkfma_b<1>(vv, HI2(ok), pkfma_b<1>(sap, HI2(ob), pkmul_b<1>(C3, HI2(ow))));
;                     const f32x2 q = pkfma_b<1>(C3, HI2(orr), pkfma_b<0>(C2, HI2(orr), pkfma_b<1>(C1, LO2(orr), pkmul_b<0>(C0, LO2(orr)))));
;                     float y0 = q.x, y1 = q.y;
;                     y0 += dppf<0xB1>(y0); y1 += dppf<0xB1>(y1);
;                     *(LAS f32x2*)(yb + ((s * 32 + (r0 >> 1)) * 8 + ((lane >> 1) & 7)) * 2) = (f32x2){y0, y1};
;                     ow = now; oa = noa; ob = nob; ok = nok; orr = norr; vv = nvv;
;                 }
	v_pk_fma_f32 v[236:237], v[168:169], v[116:117], v[236:237] op_sel_hi:[1,0,1]
	v_pk_fma_f32 v[238:239], v[168:169], v[116:117], v[238:239] op_sel:[0,1,0]
	v_pk_fma_f32 v[240:241], v[168:169], v[118:119], v[240:241] op_sel_hi:[1,0,1]
	v_pk_fma_f32 v[242:243], v[168:169], v[118:119], v[242:243] op_sel:[0,1,0]
	v_pk_fma_f32 v[244:245], v[168:169], v[120:121], v[244:245] op_sel_hi:[1,0,1]
	v_pk_fma_f32 v[246:247], v[168:169], v[120:121], v[246:247] op_sel:[0,1,0]
	v_pk_fma_f32 v[248:249], v[168:169], v[122:123], v[248:249] op_sel_hi:[1,0,1]
	v_pk_fma_f32 v[250:251], v[168:169], v[122:123], v[250:251] op_sel:[0,1,0]
	ds_read_b128 v[116:119], v252 offset:2592
	ds_read_b128 v[120:123], v252 offset:2672
	s_waitcnt lgkmcnt(9)
	v_pk_fma_f32 v[236:237], v[166:167], v[124:125], v[236:237] op_sel_hi:[1,0,1]
	v_pk_fma_f32 v[238:239], v[166:167], v[124:125], v[238:239] op_sel:[0,1,0]
	v_pk_fma_f32 v[240:241], v[166:167], v[126:127], v[240:241] op_sel_hi:[1,0,1]
	v_pk_fma_f32 v[242:243], v[166:167], v[126:127], v[242:243] op_sel:[0,1,0]
	v_pk_fma_f32 v[244:245], v[166:167], v[128:129], v[244:245] op_sel_hi:[1,0,1]
	v_pk_fma_f32 v[246:247], v[166:167], v[128:129], v[246:247] op_sel:[0,1,0]
	v_pk_fma_f32 v[248:249], v[166:167], v[130:131], v[248:249] op_sel_hi:[1,0,1]
	v_pk_fma_f32 v[250:251], v[166:167], v[130:131], v[250:251] op_sel:[0,1,0]
	ds_read_b128 v[124:127], v252 offset:2608
	ds_read_b128 v[128:131], v252 offset:2688
	ds_read_b64 v[166:167], v253 offset:512
	s_waitcnt lgkmcnt(10)
	v_pk_mul_f32 v[172:173], v[236:237], v[132:133] op_sel_hi:[1,0]
	v_pk_mul_f32 v[174:175], v[238:239], v[132:133] op_sel:[0,1]
	v_pk_fma_f32 v[172:173], v[240:241], v[134:135], v[172:173] op_sel_hi:[1,0,1]
	v_pk_fma_f32 v[174:175], v[242:243], v[134:135], v[174:175] op_sel:[0,1,0]
	v_pk_fma_f32 v[172:173], v[244:245], v[136:137], v[172:173] op_sel_hi:[1,0,1]
	v_pk_fma_f32 v[174:175], v[246:247], v[136:137], v[174:175] op_sel:[0,1,0]
	v_pk_fma_f32 v[172:173], v[248:249], v[138:139], v[172:173] op_sel_hi:[1,0,1]
	v_pk_fma_f32 v[174:175], v[250:251], v[138:139], v[174:175] op_sel:[0,1,0]
	ds_read_b128 v[132:135], v252 offset:2624
	ds_read_b128 v[136:139], v252 offset:2704
	v_pk_add_f32 v[172:173], v[172:173], v[174:175]
	ds_write_b64 v254, v[172:173] offset:2048
	s_waitcnt lgkmcnt(10)
	v_pk_mul_f32 v[168:169], v[236:237], v[100:101] op_sel_hi:[1,0]
	v_pk_mul_f32 v[170:171], v[238:239], v[100:101] op_sel:[0,1]
	v_pk_fma_f32 v[168:169], v[240:241], v[102:103], v[168:169] op_sel_hi:[1,0,1]
	v_pk_fma_f32 v[170:171], v[242:243], v[102:103], v[170:171] op_sel:[0,1,0]
	v_pk_fma_f32 v[168:169], v[244:245], v[104:105], v[168:169] op_sel_hi:[1,0,1]
	v_pk_fma_f32 v[170:171], v[246:247], v[104:105], v[170:171] op_sel:[0,1,0]
	v_pk_fma_f32 v[168:169], v[248:249], v[106:107], v[168:169] op_sel_hi:[1,0,1]
	v_pk_fma_f32 v[170:171], v[250:251], v[106:107], v[170:171] op_sel:[0,1,0]
	ds_read_b128 v[100:103], v252 offset:3856
	ds_read_b128 v[104:107], v252 offset:3936
	v_pk_add_f32 v[168:169], v[168:169], v[170:171]
	s_waitcnt lgkmcnt(10)
	v_pk_mul_f32 v[236:237], v[236:237], v[108:109] op_sel_hi:[1,0]
	v_pk_mul_f32 v[238:239], v[238:239], v[108:109] op_sel:[0,1]
	v_pk_mul_f32 v[240:241], v[240:241], v[110:111] op_sel_hi:[1,0]
	v_pk_mul_f32 v[242:243], v[242:243], v[110:111] op_sel:[0,1]
	v_pk_mul_f32 v[244:245], v[244:245], v[112:113] op_sel_hi:[1,0]
	v_pk_mul_f32 v[246:247], v[246:247], v[112:113] op_sel:[0,1]
	v_pk_mul_f32 v[248:249], v[248:249], v[114:115] op_sel_hi:[1,0]
	v_pk_mul_f32 v[250:251], v[250:251], v[114:115] op_sel:[0,1]
	v_add_f32_dpp v168, v168, v168 quad_perm:[1,0,3,2] row_mask:0xf bank_mask:0xf bound_ctrl:1
	v_add_f32_dpp v169, v169, v169 quad_perm:[1,0,3,2] row_mask:0xf bank_mask:0xf bound_ctrl:1
	ds_read_b128 v[108:111], v252 offset:3840
	v_add_f32_dpp v168, v168, v168 quad_perm:[2,3,0,1] row_mask:0xf bank_mask:0xf bound_ctrl:1
	v_add_f32_dpp v169, v169, v169 quad_perm:[2,3,0,1] row_mask:0xf bank_mask:0xf bound_ctrl:1
	ds_read_b128 v[112:115], v252 offset:3920
	v_add_f32_dpp v168, v168, v168 row_half_mirror row_mask:0xf bank_mask:0xf bound_ctrl:1
	v_add_f32_dpp v169, v169, v169 row_half_mirror row_mask:0xf bank_mask:0xf bound_ctrl:1
	s_waitcnt lgkmcnt(10)
	v_pk_fma_f32 v[236:237], v[168:169], v[116:117], v[236:237] op_sel_hi:[1,0,1]
	v_pk_fma_f32 v[238:239], v[168:169], v[116:117], v[238:239] op_sel:[0,1,0]
	v_pk_fma_f32 v[240:241], v[168:169], v[118:119], v[240:241] op_sel_hi:[1,0,1]
	v_pk_fma_f32 v[242:243], v[168:169], v[118:119], v[242:243] op_sel:[0,1,0]
	v_pk_fma_f32 v[244:245], v[168:169], v[120:121], v[244:245] op_sel_hi:[1,0,1]
	v_pk_fma_f32 v[246:247], v[168:169], v[120:121], v[246:247] op_sel:[0,1,0]
	v_pk_fma_f32 v[248:249], v[168:169], v[122:123], v[248:249] op_sel_hi:[1,0,1]
	v_pk_fma_f32 v[250:251], v[168:169], v[122:123], v[250:251] op_sel:[0,1,0]
	ds_read_b128 v[116:119], v252 offset:3872
	ds_read_b128 v[120:123], v252 offset:3952
	s_waitcnt lgkmcnt(9)
	v_pk_fma_f32 v[236:237], v[166:167], v[124:125], v[236:237] op_sel_hi:[1,0,1]
	v_pk_fma_f32 v[238:239], v[166:167], v[124:125], v[238:239] op_sel:[0,1,0]
	v_pk_fma_f32 v[240:241], v[166:167], v[126:127], v[240:241] op_sel_hi:[1,0,1]
	v_pk_fma_f32 v[242:243], v[166:167], v[126:127], v[242:243] op_sel:[0,1,0]
	v_pk_fma_f32 v[244:245], v[166:167], v[128:129], v[244:245] op_sel_hi:[1,0,1]
	v_pk_fma_f32 v[246:247], v[166:167], v[128:129], v[246:247] op_sel:[0,1,0]
	v_pk_fma_f32 v[248:249], v[166:167], v[130:131], v[248:249] op_sel_hi:[1,0,1]
	v_pk_fma_f32 v[250:251], v[166:167], v[130:131], v[250:251] op_sel:[0,1,0]
	ds_read_b128 v[124:127], v252 offset:3888
	ds_read_b128 v[128:131], v252 offset:3968
	ds_read_b64 v[166:167], v253 offset:768
	s_waitcnt lgkmcnt(10)
; #define LAS __attribute__((address_space(3)))
; template <int CTRL> __device__ __forceinline__ float dppf(float v) { return __builtin_bit_cast(float, __builtin_amdgcn_update_dpp(0, __builtin_bit_cast(int, v), CTRL, 0xF, 0xF, true)); }
; #define LO2(v) __builtin_shufflevector(v, v, 0, 1)
; #define HI2(v) __builtin_shufflevector(v, v, 2, 3)
; __device__ __forceinline__ void phase_scan(const Args& a, LAS unsigned char* lds) {
;     ...
;                 for (int s = 0; s < TC; ++s) {
;                     const LAS float* o = obase + (s + 1) * 320;
;                     const f32x4 now = *(const LAS f32x4*)(o), noa = *(const LAS f32x4*)(o + 4), nob = *(const LAS f32x4*)(o + 8), nok = *(const LAS f32x4*)(o + 12), norr = *(const LAS f32x4*)(o + 16);
;                     const f32x2 nvv = *(const LAS f32x2*)(vbase + (s + 1) * 64);
;                     const f32x2 p = pkfma_b<1>(C3, HI2(oa), pkfma_b<0>(C2, HI2(oa), pkfma_b<1>(C1, LO2(oa), pkmul_b<0>(C0, LO2(oa)))));
;                     float sa0 = p.x, sa1 = p.y;
;                     sa0 = reduce16(sa0); asm volatile("" : "+v"(sa0)); sa1 = reduce16(sa1);
;                     const f32x2 sap = {sa0, sa1};
;                     C0 = pkfma_b<0>(vv, LO2(ok), pkfma_b<0>(sap, LO2(ob), pkmul_b<0>(C0, LO2(ow))));
;                     C1 = pkfma_b<1>(vv, LO2(ok), pkfma_b<1>(sap, LO2(ob), pkmul_b<1>(C1, LO2(ow))));
;                     C2 = pkfma_b<0>(vv, HI2(ok), pkfma_b<0>(sap, HI2(ob), pkmul_b<0>(C2, HI2(ow))));
;                     C3 = pkfma_b<1>(vv, HI2(ok), pkfma_b<1>(sap, HI2(ob), pkmul_b<1>(C3, HI2(ow))));
;                     const f32x2 q = pkfma_b<1>(C3, HI2(orr), pkfma_b<0>(C2, HI2(orr), pkfma_b<1>(C1, LO2(orr), pkmul_b<0>(C0, LO2(orr)))));
;                     float y0 = q.x, y1 = q.y;
;                     y0 += dppf<0xB1>(y0); y1 += dppf<0xB1>(y1);
;                     *(LAS f32x2*)(yb + ((s * 32 + (r0 >> 1)) * 8 + ((lane >> 1) & 7)) * 2) = (f32x2){y0, y1};
;                     ow = now; oa = noa; ob = nob; ok = nok; orr = norr; vv = nvv;
;                 }
	v_pk_mul_f32 v[172:173], v[236:237], v[132:133] op_sel_hi:[1,0]
	v_pk_mul_f32 v[174:175], v[238:239], v[132:133] op_sel:[0,1]
	v_pk_fma_f32 v[172:173], v[240:241], v[134:135], v[172:173] op_sel_hi:[1,0,1]
	v_pk_fma_f32 v[174:175], v[242:243], v[134:135], v[174:175] op_sel:[0,1,0]
	v_pk_fma_f32 v[172:173], v[244:245], v[136:137], v[172:173] op_sel_hi:[1,0,1]
	v_pk_fma_f32 v[174:175], v[246:247], v[136:137], v[174:175] op_sel:[0,1,0]
	v_pk_fma_f32 v[172:173], v[248:249], v[138:139], v[172:173] op_sel_hi:[1,0,1]
	v_pk_fma_f32 v[174:175], v[250:251], v[138:139], v[174:175] op_sel:[0,1,0]
	ds_read_b128 v[132:135], v252 offset:3904
	ds_read_b128 v[136:139], v252 offset:3984
	v_pk_add_f32 v[172:173], v[172:173], v[174:175]
	ds_write_b64 v254, v[172:173] offset:4096
	s_waitcnt lgkmcnt(10)
	v_pk_mul_f32 v[168:169], v[236:237], v[100:101] op_sel_hi:[1,0]
	v_pk_mul_f32 v[170:171], v[238:239], v[100:101] op_sel:[0,1]
	v_pk_fma_f32 v[168:169], v[240:241], v[102:103], v[168:169] op_sel_hi:[1,0,1]
	v_pk_fma_f32 v[170:171], v[242:243], v[102:103], v[170:171] op_sel:[0,1,0]
	v_pk_fma_f32 v[168:169], v[244:245], v[104:105], v[168:169] op_sel_hi:[1,0,1]
	v_pk_fma_f32 v[170:171], v[246:247], v[104:105], v[170:171] op_sel:[0,1,0]
	v_pk_fma_f32 v[168:169], v[248:249], v[106:107], v[168:169] op_sel_hi:[1,0,1]
	v_pk_fma_f32 v[170:171], v[250:251], v[106:107], v[170:171] op_sel:[0,1,0]
	ds_read_b128 v[100:103], v252 offset:5136
	ds_read_b128 v[104:107], v252 offset:5216
	v_pk_add_f32 v[168:169], v[168:169], v[170:171]
	s_waitcnt lgkmcnt(10)
	v_pk_mul_f32 v[236:237], v[236:237], v[108:109] op_sel_hi:[1,0]
	v_pk_mul_f32 v[238:239], v[238:239], v[108:109] op_sel:[0,1]
	v_pk_mul_f32 v[240:241], v[240:241], v[110:111] op_sel_hi:[1,0]
	v_pk_mul_f32 v[242:243], v[242:243], v[110:111] op_sel:[0,1]
	v_pk_mul_f32 v[244:245], v[244:245], v[112:113] op_sel_hi:[1,0]
	v_pk_mul_f32 v[246:247], v[246:247], v[112:113] op_sel:[0,1]
	v_pk_mul_f32 v[248:249], v[248:249], v[114:115] op_sel_hi:[1,0]
	v_pk_mul_f32 v[250:251], v[250:251], v[114:115] op_sel:[0,1]
	v_add_f32_dpp v168, v168, v168 quad_perm:[1,0,3,2] row_mask:0xf bank_mask:0xf bound_ctrl:1
	v_add_f32_dpp v169, v169, v169 quad_perm:[1,0,3,2] row_mask:0xf bank_mask:0xf bound_ctrl:1
	ds_read_b128 v[108:111], v252 offset:5120
	v_add_f32_dpp v168, v168, v168 quad_perm:[2,3,0,1] row_mask:0xf bank_mask:0xf bound_ctrl:1
	v_add_f32_dpp v169, v169, v169 quad_perm:[2,3,0,1] row_mask:0xf bank_mask:0xf bound_ctrl:1
	ds_read_b128 v[112:115], v252 offset:5200
	v_add_f32_dpp v168, v168, v168 row_half_mirror row_mask:0xf bank_mask:0xf bound_ctrl:1
	v_add_f32_dpp v169, v169, v169 row_half_mirror row_mask:0xf bank_mask:0xf bound_ctrl:1
	s_waitcnt lgkmcnt(10)
	v_pk_fma_f32 v[236:237], v[168:169], v[116:117], v[236:237] op_sel_hi:[1,0,1]
	v_pk_fma_f32 v[238:239], v[168:169], v[116:117], v[238:239] op_sel:[0,1,0]
	v_pk_fma_f32 v[240:241], v[168:169], v[118:119], v[240:241] op_sel_hi:[1,0,1]
	v_pk_fma_f32 v[242:243], v[168:169], v[118:119], v[242:243] op_sel:[0,1,0]
	v_pk_fma_f32 v[244:245], v[168:169], v[120:121], v[244:245] op_sel_hi:[1,0,1]
	v_pk_fma_f32 v[246:247], v[168:169], v[120:121], v[246:247] op_sel:[0,1,0]
	v_pk_fma_f32 v[248:249], v[168:169], v[122:123], v[248:249] op_sel_hi:[1,0,1]
	v_pk_fma_f32 v[250:251], v[168:169], v[122:123], v[250:251] op_sel:[0,1,0]
	ds_read_b128 v[116:119], v252 offset:5152
	ds_read_b128 v[120:123], v252 offset:5232
	s_waitcnt lgkmcnt(9)
	v_pk_fma_f32 v[236:237], v[166:167], v[124:125], v[236:237] op_sel_hi:[1,0,1]
	v_pk_fma_f32 v[238:239], v[166:167], v[124:125], v[238:239] op_sel:[0,1,0]
	v_pk_fma_f32 v[240:241], v[166:167], v[126:127], v[240:241] op_sel_hi:[1,0,1]
	v_pk_fma_f32 v[242:243], v[166:167], v[126:127], v[242:243] op_sel:[0,1,0]
	v_pk_fma_f32 v[244:245], v[166:167], v[128:129], v[244:245] op_sel_hi:[1,0,1]
	v_pk_fma_f32 v[246:247], v[166:167], v[128:129], v[246:247] op_sel:[0,1,0]
	v_pk_fma_f32 v[248:249], v[166:167], v[130:131], v[248:249] op_sel_hi:[1,0,1]
	v_pk_fma_f32 v[250:251], v[166:167], v[130:131], v[250:251] op_sel:[0,1,0]
	ds_read_b128 v[124:127], v252 offset:5168
	ds_read_b128 v[128:131], v252 offset:5248
	ds_read_b64 v[166:167], v253 offset:1024
	s_waitcnt lgkmcnt(10)
	v_pk_mul_f32 v[172:173], v[236:237], v[132:133] op_sel_hi:[1,0]
	v_pk_mul_f32 v[174:175], v[238:239], v[132:133] op_sel:[0,1]
	v_pk_fma_f32 v[172:173], v[240:241], v[134:135], v[172:173] op_sel_hi:[1,0,1]
	v_pk_fma_f32 v[174:175], v[242:243], v[134:135], v[174:175] op_sel:[0,1,0]
	v_pk_fma_f32 v[172:173], v[244:245], v[136:137], v[172:173] op_sel_hi:[1,0,1]
	v_pk_fma_f32 v[174:175], v[246:247], v[136:137], v[174:175] op_sel:[0,1,0]
	v_pk_fma_f32 v[172:173], v[248:249], v[138:139], v[172:173] op_sel_hi:[1,0,1]
	v_pk_fma_f32 v[174:175], v[250:251], v[138:139], v[174:175] op_sel:[0,1,0]
	ds_read_b128 v[132:135], v252 offset:5184
	ds_read_b128 v[136:139], v252 offset:5264
	v_pk_add_f32 v[172:173], v[172:173], v[174:175]
	ds_write_b64 v254, v[172:173] offset:6144
	s_waitcnt lgkmcnt(10)
	v_pk_mul_f32 v[168:169], v[236:237], v[100:101] op_sel_hi:[1,0]
	v_pk_mul_f32 v[170:171], v[238:239], v[100:101] op_sel:[0,1]
	v_pk_fma_f32 v[168:169], v[240:241], v[102:103], v[168:169] op_sel_hi:[1,0,1]
	v_pk_fma_f32 v[170:171], v[242:243], v[102:103], v[170:171] op_sel:[0,1,0]
	v_pk_fma_f32 v[168:169], v[244:245], v[104:105], v[168:169] op_sel_hi:[1,0,1]
	v_pk_fma_f32 v[170:171], v[246:247], v[104:105], v[170:171] op_sel:[0,1,0]
	v_pk_fma_f32 v[168:169], v[248:249], v[106:107], v[168:169] op_sel_hi:[1,0,1]
	v_pk_fma_f32 v[170:171], v[250:251], v[106:107], v[170:171] op_sel:[0,1,0]
	ds_read_b128 v[100:103], v252 offset:6416
	ds_read_b128 v[104:107], v252 offset:6496
	v_pk_add_f32 v[168:169], v[168:169], v[170:171]
	s_waitcnt lgkmcnt(10)
; #define LAS __attribute__((address_space(3)))
; template <int CTRL> __device__ __forceinline__ float dppf(float v) { return __builtin_bit_cast(float, __builtin_amdgcn_update_dpp(0, __builtin_bit_cast(int, v), CTRL, 0xF, 0xF, true)); }
; #define LO2(v) __builtin_shufflevector(v, v, 0, 1)
; #define HI2(v) __builtin_shufflevector(v, v, 2, 3)
; __device__ __forceinline__ void phase_scan(const Args& a, LAS unsigned char* lds) {
;     ...
;                 for (int s = 0; s < TC; ++s) {
;                     const LAS float* o = obase + (s + 1) * 320;
;                     const f32x4 now = *(const LAS f32x4*)(o), noa = *(const LAS f32x4*)(o + 4), nob = *(const LAS f32x4*)(o + 8), nok = *(const LAS f32x4*)(o + 12), norr = *(const LAS f32x4*)(o + 16);
;                     const f32x2 nvv = *(const LAS f32x2*)(vbase + (s + 1) * 64);
;                     const f32x2 p = pkfma_b<1>(C3, HI2(oa), pkfma_b<0>(C2, HI2(oa), pkfma_b<1>(C1, LO2(oa), pkmul_b<0>(C0, LO2(oa)))));
;                     float sa0 = p.x, sa1 = p.y;
;                     sa0 = reduce16(sa0); asm volatile("" : "+v"(sa0)); sa1 = reduce16(sa1);
;                     const f32x2 sap = {sa0, sa1};
;                     C0 = pkfma_b<0>(vv, LO2(ok), pkfma_b<0>(sap, LO2(ob), pkmul_b<0>(C0, LO2(ow))));
;                     C1 = pkfma_b<1>(vv, LO2(ok), pkfma_b<1>(sap, LO2(ob), pkmul_b<1>(C1, LO2(ow))));
;                     C2 = pkfma_b<0>(vv, HI2(ok), pkfma_b<0>(sap, HI2(ob), pkmul_b<0>(C2, HI2(ow))));
;                     C3 = pkfma_b<1>(vv, HI2(ok), pkfma_b<1>(sap, HI2(ob), pkmul_b<1>(C3, HI2(ow))));
;                     const f32x2 q = pkfma_b<1>(C3, HI2(orr), pkfma_b<0>(C2, HI2(orr), pkfma_b<1>(C1, LO2(orr), pkmul_b<0>(C0, LO2(orr)))));
;                     float y0 = q.x, y1 = q.y;
;                     y0 += dppf<0xB1>(y0); y1 += dppf<0xB1>(y1);
;                     *(LAS f32x2*)(yb + ((s * 32 + (r0 >> 1)) * 8 + ((lane >> 1) & 7)) * 2) = (f32x2){y0, y1};
;                     ow = now; oa = noa; ob = nob; ok = nok; orr = norr; vv = nvv;
;                 }
	v_pk_mul_f32 v[236:237], v[236:237], v[108:109] op_sel_hi:[1,0]
	v_pk_mul_f32 v[238:239], v[238:239], v[108:109] op_sel:[0,1]
	v_pk_mul_f32 v[240:241], v[240:241], v[110:111] op_sel_hi:[1,0]
	v_pk_mul_f32 v[242:243], v[242:243], v[110:111] op_sel:[0,1]
	v_pk_mul_f32 v[244:245], v[244:245], v[112:113] op_sel_hi:[1,0]
	v_pk_mul_f32 v[246:247], v[246:247], v[112:113] op_sel:[0,1]
	v_pk_mul_f32 v[248:249], v[248:249], v[114:115] op_sel_hi:[1,0]
	v_pk_mul_f32 v[250:251], v[250:251], v[114:115] op_sel:[0,1]
	v_add_f32_dpp v168, v168, v168 quad_perm:[1,0,3,2] row_mask:0xf bank_mask:0xf bound_ctrl:1
	v_add_f32_dpp v169, v169, v169 quad_perm:[1,0,3,2] row_mask:0xf bank_mask:0xf bound_ctrl:1
	ds_read_b128 v[108:111], v252 offset:6400
	v_add_f32_dpp v168, v168, v168 quad_perm:[2,3,0,1] row_mask:0xf bank_mask:0xf bound_ctrl:1
	v_add_f32_dpp v169, v169, v169 quad_perm:[2,3,0,1] row_mask:0xf bank_mask:0xf bound_ctrl:1
	ds_read_b128 v[112:115], v252 offset:6480
	v_add_f32_dpp v168, v168, v168 row_half_mirror row_mask:0xf bank_mask:0xf bound_ctrl:1
	v_add_f32_dpp v169, v169, v169 row_half_mirror row_mask:0xf bank_mask:0xf bound_ctrl:1
	s_waitcnt lgkmcnt(10)
	v_pk_fma_f32 v[236:237], v[168:169], v[116:117], v[236:237] op_sel_hi:[1,0,1]
	v_pk_fma_f32 v[238:239], v[168:169], v[116:117], v[238:239] op_sel:[0,1,0]
	v_pk_fma_f32 v[240:241], v[168:169], v[118:119], v[240:241] op_sel_hi:[1,0,1]
	v_pk_fma_f32 v[242:243], v[168:169], v[118:119], v[242:243] op_sel:[0,1,0]
	v_pk_fma_f32 v[244:245], v[168:169], v[120:121], v[244:245] op_sel_hi:[1,0,1]
	v_pk_fma_f32 v[246:247], v[168:169], v[120:121], v[246:247] op_sel:[0,1,0]
	v_pk_fma_f32 v[248:249], v[168:169], v[122:123], v[248:249] op_sel_hi:[1,0,1]
	v_pk_fma_f32 v[250:251], v[168:169], v[122:123], v[250:251] op_sel:[0,1,0]
	ds_read_b128 v[116:119], v252 offset:6432
	ds_read_b128 v[120:123], v252 offset:6512
	s_waitcnt lgkmcnt(9)
	v_pk_fma_f32 v[236:237], v[166:167], v[124:125], v[236:237] op_sel_hi:[1,0,1]
	v_pk_fma_f32 v[238:239], v[166:167], v[124:125], v[238:239] op_sel:[0,1,0]
	v_pk_fma_f32 v[240:241], v[166:167], v[126:127], v[240:241] op_sel_hi:[1,0,1]
	v_pk_fma_f32 v[242:243], v[166:167], v[126:127], v[242:243] op_sel:[0,1,0]
	v_pk_fma_f32 v[244:245], v[166:167], v[128:129], v[244:245] op_sel_hi:[1,0,1]
	v_pk_fma_f32 v[246:247], v[166:167], v[128:129], v[246:247] op_sel:[0,1,0]
	v_pk_fma_f32 v[248:249], v[166:167], v[130:131], v[248:249] op_sel_hi:[1,0,1]
	v_pk_fma_f32 v[250:251], v[166:167], v[130:131], v[250:251] op_sel:[0,1,0]
	ds_read_b128 v[124:127], v252 offset:6448
	ds_read_b128 v[128:131], v252 offset:6528
	ds_read_b64 v[166:167], v253 offset:1280
	s_waitcnt lgkmcnt(10)
	v_pk_mul_f32 v[172:173], v[236:237], v[132:133] op_sel_hi:[1,0]
	v_pk_mul_f32 v[174:175], v[238:239], v[132:133] op_sel:[0,1]
	v_pk_fma_f32 v[172:173], v[240:241], v[134:135], v[172:173] op_sel_hi:[1,0,1]
	v_pk_fma_f32 v[174:175], v[242:243], v[134:135], v[174:175] op_sel:[0,1,0]
	v_pk_fma_f32 v[172:173], v[244:245], v[136:137], v[172:173] op_sel_hi:[1,0,1]
	v_pk_fma_f32 v[174:175], v[246:247], v[136:137], v[174:175] op_sel:[0,1,0]
	v_pk_fma_f32 v[172:173], v[248:249], v[138:139], v[172:173] op_sel_hi:[1,0,1]
	v_pk_fma_f32 v[174:175], v[250:251], v[138:139], v[174:175] op_sel:[0,1,0]
	ds_read_b128 v[132:135], v252 offset:6464
	ds_read_b128 v[136:139], v252 offset:6544
	v_pk_add_f32 v[172:173], v[172:173], v[174:175]
	ds_write_b64 v254, v[172:173] offset:8192
	s_waitcnt lgkmcnt(10)
	v_pk_mul_f32 v[168:169], v[236:237], v[100:101] op_sel_hi:[1,0]
	v_pk_mul_f32 v[170:171], v[238:239], v[100:101] op_sel:[0,1]
	v_pk_fma_f32 v[168:169], v[240:241], v[102:103], v[168:169] op_sel_hi:[1,0,1]
	v_pk_fma_f32 v[170:171], v[242:243], v[102:103], v[170:171] op_sel:[0,1,0]
	v_pk_fma_f32 v[168:169], v[244:245], v[104:105], v[168:169] op_sel_hi:[1,0,1]
	v_pk_fma_f32 v[170:171], v[246:247], v[104:105], v[170:171] op_sel:[0,1,0]
	v_pk_fma_f32 v[168:169], v[248:249], v[106:107], v[168:169] op_sel_hi:[1,0,1]
	v_pk_fma_f32 v[170:171], v[250:251], v[106:107], v[170:171] op_sel:[0,1,0]
	ds_read_b128 v[100:103], v252 offset:7696
	ds_read_b128 v[104:107], v252 offset:7776
	v_pk_add_f32 v[168:169], v[168:169], v[170:171]
	s_waitcnt lgkmcnt(10)
	v_pk_mul_f32 v[236:237], v[236:237], v[108:109] op_sel_hi:[1,0]
	v_pk_mul_f32 v[238:239], v[238:239], v[108:109] op_sel:[0,1]
	v_pk_mul_f32 v[240:241], v[240:241], v[110:111] op_sel_hi:[1,0]
	v_pk_mul_f32 v[242:243], v[242:243], v[110:111] op_sel:[0,1]
	v_pk_mul_f32 v[244:245], v[244:245], v[112:113] op_sel_hi:[1,0]
	v_pk_mul_f32 v[246:247], v[246:247], v[112:113] op_sel:[0,1]
	v_pk_mul_f32 v[248:249], v[248:249], v[114:115] op_sel_hi:[1,0]
	v_pk_mul_f32 v[250:251], v[250:251], v[114:115] op_sel:[0,1]
	v_add_f32_dpp v168, v168, v168 quad_perm:[1,0,3,2] row_mask:0xf bank_mask:0xf bound_ctrl:1
	v_add_f32_dpp v169, v169, v169 quad_perm:[1,0,3,2] row_mask:0xf bank_mask:0xf bound_ctrl:1
	ds_read_b128 v[108:111], v252 offset:7680
	v_add_f32_dpp v168, v168, v168 quad_perm:[2,3,0,1] row_mask:0xf bank_mask:0xf bound_ctrl:1
	v_add_f32_dpp v169, v169, v169 quad_perm:[2,3,0,1] row_mask:0xf bank_mask:0xf bound_ctrl:1
	ds_read_b128 v[112:115], v252 offset:7760
	v_add_f32_dpp v168, v168, v168 row_half_mirror row_mask:0xf bank_mask:0xf bound_ctrl:1
	v_add_f32_dpp v169, v169, v169 row_half_mirror row_mask:0xf bank_mask:0xf bound_ctrl:1
	s_waitcnt lgkmcnt(10)
; #define LAS __attribute__((address_space(3)))
; template <int CTRL> __device__ __forceinline__ float dppf(float v) { return __builtin_bit_cast(float, __builtin_amdgcn_update_dpp(0, __builtin_bit_cast(int, v), CTRL, 0xF, 0xF, true)); }
; #define LO2(v) __builtin_shufflevector(v, v, 0, 1)
; #define HI2(v) __builtin_shufflevector(v, v, 2, 3)
; __device__ __forceinline__ void phase_scan(const Args& a, LAS unsigned char* lds) {
;     ...
;                 for (int s = 0; s < TC; ++s) {
;                     const LAS float* o = obase + (s + 1) * 320;
;                     const f32x4 now = *(const LAS f32x4*)(o), noa = *(const LAS f32x4*)(o + 4), nob = *(const LAS f32x4*)(o + 8), nok = *(const LAS f32x4*)(o + 12), norr = *(const LAS f32x4*)(o + 16);
;                     const f32x2 nvv = *(const LAS f32x2*)(vbase + (s + 1) * 64);
;                     const f32x2 p = pkfma_b<1>(C3, HI2(oa), pkfma_b<0>(C2, HI2(oa), pkfma_b<1>(C1, LO2(oa), pkmul_b<0>(C0, LO2(oa)))));
;                     float sa0 = p.x, sa1 = p.y;
;                     sa0 = reduce16(sa0); asm volatile("" : "+v"(sa0)); sa1 = reduce16(sa1);
;                     const f32x2 sap = {sa0, sa1};
;                     C0 = pkfma_b<0>(vv, LO2(ok), pkfma_b<0>(sap, LO2(ob), pkmul_b<0>(C0, LO2(ow))));
;                     C1 = pkfma_b<1>(vv, LO2(ok), pkfma_b<1>(sap, LO2(ob), pkmul_b<1>(C1, LO2(ow))));
;                     C2 = pkfma_b<0>(vv, HI2(ok), pkfma_b<0>(sap, HI2(ob), pkmul_b<0>(C2, HI2(ow))));
;                     C3 = pkfma_b<1>(vv, HI2(ok), pkfma_b<1>(sap, HI2(ob), pkmul_b<1>(C3, HI2(ow))));
;                     const f32x2 q = pkfma_b<1>(C3, HI2(orr), pkfma_b<0>(C2, HI2(orr), pkfma_b<1>(C1, LO2(orr), pkmul_b<0>(C0, LO2(orr)))));
;                     float y0 = q.x, y1 = q.y;
;                     y0 += dppf<0xB1>(y0); y1 += dppf<0xB1>(y1);
;                     *(LAS f32x2*)(yb + ((s * 32 + (r0 >> 1)) * 8 + ((lane >> 1) & 7)) * 2) = (f32x2){y0, y1};
;                     ow = now; oa = noa; ob = nob; ok = nok; orr = norr; vv = nvv;
;                 }
	v_pk_fma_f32 v[236:237], v[168:169], v[116:117], v[236:237] op_sel_hi:[1,0,1]
	v_pk_fma_f32 v[238:239], v[168:169], v[116:117], v[238:239] op_sel:[0,1,0]
	v_pk_fma_f32 v[240:241], v[168:169], v[118:119], v[240:241] op_sel_hi:[1,0,1]
	v_pk_fma_f32 v[242:243], v[168:169], v[118:119], v[242:243] op_sel:[0,1,0]
	v_pk_fma_f32 v[244:245], v[168:169], v[120:121], v[244:245] op_sel_hi:[1,0,1]
	v_pk_fma_f32 v[246:247], v[168:169], v[120:121], v[246:247] op_sel:[0,1,0]
	v_pk_fma_f32 v[248:249], v[168:169], v[122:123], v[248:249] op_sel_hi:[1,0,1]
	v_pk_fma_f32 v[250:251], v[168:169], v[122:123], v[250:251] op_sel:[0,1,0]
	ds_read_b128 v[116:119], v252 offset:7712
	ds_read_b128 v[120:123], v252 offset:7792
	s_waitcnt lgkmcnt(9)
	v_pk_fma_f32 v[236:237], v[166:167], v[124:125], v[236:237] op_sel_hi:[1,0,1]
	v_pk_fma_f32 v[238:239], v[166:167], v[124:125], v[238:239] op_sel:[0,1,0]
	v_pk_fma_f32 v[240:241], v[166:167], v[126:127], v[240:241] op_sel_hi:[1,0,1]
	v_pk_fma_f32 v[242:243], v[166:167], v[126:127], v[242:243] op_sel:[0,1,0]
	v_pk_fma_f32 v[244:245], v[166:167], v[128:129], v[244:245] op_sel_hi:[1,0,1]
	v_pk_fma_f32 v[246:247], v[166:167], v[128:129], v[246:247] op_sel:[0,1,0]
	v_pk_fma_f32 v[248:249], v[166:167], v[130:131], v[248:249] op_sel_hi:[1,0,1]
	v_pk_fma_f32 v[250:251], v[166:167], v[130:131], v[250:251] op_sel:[0,1,0]
	ds_read_b128 v[124:127], v252 offset:7728
	ds_read_b128 v[128:131], v252 offset:7808
	ds_read_b64 v[166:167], v253 offset:1536
	s_waitcnt lgkmcnt(10)
	v_pk_mul_f32 v[172:173], v[236:237], v[132:133] op_sel_hi:[1,0]
	v_pk_mul_f32 v[174:175], v[238:239], v[132:133] op_sel:[0,1]
	v_pk_fma_f32 v[172:173], v[240:241], v[134:135], v[172:173] op_sel_hi:[1,0,1]
	v_pk_fma_f32 v[174:175], v[242:243], v[134:135], v[174:175] op_sel:[0,1,0]
	v_pk_fma_f32 v[172:173], v[244:245], v[136:137], v[172:173] op_sel_hi:[1,0,1]
	v_pk_fma_f32 v[174:175], v[246:247], v[136:137], v[174:175] op_sel:[0,1,0]
	v_pk_fma_f32 v[172:173], v[248:249], v[138:139], v[172:173] op_sel_hi:[1,0,1]
	v_pk_fma_f32 v[174:175], v[250:251], v[138:139], v[174:175] op_sel:[0,1,0]
	ds_read_b128 v[132:135], v252 offset:7744
	ds_read_b128 v[136:139], v252 offset:7824
	v_pk_add_f32 v[172:173], v[172:173], v[174:175]
	ds_write_b64 v254, v[172:173] offset:10240
	s_waitcnt lgkmcnt(10)
	v_pk_mul_f32 v[168:169], v[236:237], v[100:101] op_sel_hi:[1,0]
	v_pk_mul_f32 v[170:171], v[238:239], v[100:101] op_sel:[0,1]
	v_pk_fma_f32 v[168:169], v[240:241], v[102:103], v[168:169] op_sel_hi:[1,0,1]
	v_pk_fma_f32 v[170:171], v[242:243], v[102:103], v[170:171] op_sel:[0,1,0]
	v_pk_fma_f32 v[168:169], v[244:245], v[104:105], v[168:169] op_sel_hi:[1,0,1]
	v_pk_fma_f32 v[170:171], v[246:247], v[104:105], v[170:171] op_sel:[0,1,0]
	v_pk_fma_f32 v[168:169], v[248:249], v[106:107], v[168:169] op_sel_hi:[1,0,1]
	v_pk_fma_f32 v[170:171], v[250:251], v[106:107], v[170:171] op_sel:[0,1,0]
	ds_read_b128 v[100:103], v252 offset:8976
	ds_read_b128 v[104:107], v252 offset:9056
	v_pk_add_f32 v[168:169], v[168:169], v[170:171]
	s_waitcnt lgkmcnt(10)
	v_pk_mul_f32 v[236:237], v[236:237], v[108:109] op_sel_hi:[1,0]
	v_pk_mul_f32 v[238:239], v[238:239], v[108:109] op_sel:[0,1]
	v_pk_mul_f32 v[240:241], v[240:241], v[110:111] op_sel_hi:[1,0]
	v_pk_mul_f32 v[242:243], v[242:243], v[110:111] op_sel:[0,1]
	v_pk_mul_f32 v[244:245], v[244:245], v[112:113] op_sel_hi:[1,0]
	v_pk_mul_f32 v[246:247], v[246:247], v[112:113] op_sel:[0,1]
	v_pk_mul_f32 v[248:249], v[248:249], v[114:115] op_sel_hi:[1,0]
	v_pk_mul_f32 v[250:251], v[250:251], v[114:115] op_sel:[0,1]
	v_add_f32_dpp v168, v168, v168 quad_perm:[1,0,3,2] row_mask:0xf bank_mask:0xf bound_ctrl:1
	v_add_f32_dpp v169, v169, v169 quad_perm:[1,0,3,2] row_mask:0xf bank_mask:0xf bound_ctrl:1
	ds_read_b128 v[108:111], v252 offset:8960
	v_add_f32_dpp v168, v168, v168 quad_perm:[2,3,0,1] row_mask:0xf bank_mask:0xf bound_ctrl:1
	v_add_f32_dpp v169, v169, v169 quad_perm:[2,3,0,1] row_mask:0xf bank_mask:0xf bound_ctrl:1
	ds_read_b128 v[112:115], v252 offset:9040
	v_add_f32_dpp v168, v168, v168 row_half_mirror row_mask:0xf bank_mask:0xf bound_ctrl:1
	v_add_f32_dpp v169, v169, v169 row_half_mirror row_mask:0xf bank_mask:0xf bound_ctrl:1
	s_waitcnt lgkmcnt(10)
	v_pk_fma_f32 v[236:237], v[168:169], v[116:117], v[236:237] op_sel_hi:[1,0,1]
	v_pk_fma_f32 v[238:239], v[168:169], v[116:117], v[238:239] op_sel:[0,1,0]
	v_pk_fma_f32 v[240:241], v[168:169], v[118:119], v[240:241] op_sel_hi:[1,0,1]
	v_pk_fma_f32 v[242:243], v[168:169], v[118:119], v[242:243] op_sel:[0,1,0]
	v_pk_fma_f32 v[244:245], v[168:169], v[120:121], v[244:245] op_sel_hi:[1,0,1]
	v_pk_fma_f32 v[246:247], v[168:169], v[120:121], v[246:247] op_sel:[0,1,0]
	v_pk_fma_f32 v[248:249], v[168:169], v[122:123], v[248:249] op_sel_hi:[1,0,1]
	v_pk_fma_f32 v[250:251], v[168:169], v[122:123], v[250:251] op_sel:[0,1,0]
	ds_read_b128 v[116:119], v252 offset:8992
	ds_read_b128 v[120:123], v252 offset:9072
	s_waitcnt lgkmcnt(9)
	v_pk_fma_f32 v[236:237], v[166:167], v[124:125], v[236:237] op_sel_hi:[1,0,1]
	v_pk_fma_f32 v[238:239], v[166:167], v[124:125], v[238:239] op_sel:[0,1,0]
	v_pk_fma_f32 v[240:241], v[166:167], v[126:127], v[240:241] op_sel_hi:[1,0,1]
	v_pk_fma_f32 v[242:243], v[166:167], v[126:127], v[242:243] op_sel:[0,1,0]
	v_pk_fma_f32 v[244:245], v[166:167], v[128:129], v[244:245] op_sel_hi:[1,0,1]
	v_pk_fma_f32 v[246:247], v[166:167], v[128:129], v[246:247] op_sel:[0,1,0]
	v_pk_fma_f32 v[248:249], v[166:167], v[130:131], v[248:249] op_sel_hi:[1,0,1]
	v_pk_fma_f32 v[250:251], v[166:167], v[130:131], v[250:251] op_sel:[0,1,0]
	ds_read_b128 v[124:127], v252 offset:9008
	ds_read_b128 v[128:131], v252 offset:9088
	ds_read_b64 v[166:167], v253 offset:1792
	s_waitcnt lgkmcnt(10)
; #define LAS __attribute__((address_space(3)))
; template <int CTRL> __device__ __forceinline__ float dppf(float v) { return __builtin_bit_cast(float, __builtin_amdgcn_update_dpp(0, __builtin_bit_cast(int, v), CTRL, 0xF, 0xF, true)); }
; #define LO2(v) __builtin_shufflevector(v, v, 0, 1)
; #define HI2(v) __builtin_shufflevector(v, v, 2, 3)
; __device__ __forceinline__ void phase_scan(const Args& a, LAS unsigned char* lds) {
;     ...
;                 for (int s = 0; s < TC; ++s) {
;                     const LAS float* o = obase + (s + 1) * 320;
;                     const f32x4 now = *(const LAS f32x4*)(o), noa = *(const LAS f32x4*)(o + 4), nob = *(const LAS f32x4*)(o + 8), nok = *(const LAS f32x4*)(o + 12), norr = *(const LAS f32x4*)(o + 16);
;                     const f32x2 nvv = *(const LAS f32x2*)(vbase + (s + 1) * 64);
;                     const f32x2 p = pkfma_b<1>(C3, HI2(oa), pkfma_b<0>(C2, HI2(oa), pkfma_b<1>(C1, LO2(oa), pkmul_b<0>(C0, LO2(oa)))));
;                     float sa0 = p.x, sa1 = p.y;
;                     sa0 = reduce16(sa0); asm volatile("" : "+v"(sa0)); sa1 = reduce16(sa1);
;                     const f32x2 sap = {sa0, sa1};
;                     C0 = pkfma_b<0>(vv, LO2(ok), pkfma_b<0>(sap, LO2(ob), pkmul_b<0>(C0, LO2(ow))));
;                     C1 = pkfma_b<1>(vv, LO2(ok), pkfma_b<1>(sap, LO2(ob), pkmul_b<1>(C1, LO2(ow))));
;                     C2 = pkfma_b<0>(vv, HI2(ok), pkfma_b<0>(sap, HI2(ob), pkmul_b<0>(C2, HI2(ow))));
;                     C3 = pkfma_b<1>(vv, HI2(ok), pkfma_b<1>(sap, HI2(ob), pkmul_b<1>(C3, HI2(ow))));
;                     const f32x2 q = pkfma_b<1>(C3, HI2(orr), pkfma_b<0>(C2, HI2(orr), pkfma_b<1>(C1, LO2(orr), pkmul_b<0>(C0, LO2(orr)))));
;                     float y0 = q.x, y1 = q.y;
;                     y0 += dppf<0xB1>(y0); y1 += dppf<0xB1>(y1);
;                     *(LAS f32x2*)(yb + ((s * 32 + (r0 >> 1)) * 8 + ((lane >> 1) & 7)) * 2) = (f32x2){y0, y1};
;                     ow = now; oa = noa; ob = nob; ok = nok; orr = norr; vv = nvv;
;                 }
	v_pk_mul_f32 v[172:173], v[236:237], v[132:133] op_sel_hi:[1,0]
	v_pk_mul_f32 v[174:175], v[238:239], v[132:133] op_sel:[0,1]
	v_pk_fma_f32 v[172:173], v[240:241], v[134:135], v[172:173] op_sel_hi:[1,0,1]
	v_pk_fma_f32 v[174:175], v[242:243], v[134:135], v[174:175] op_sel:[0,1,0]
	v_pk_fma_f32 v[172:173], v[244:245], v[136:137], v[172:173] op_sel_hi:[1,0,1]
	v_pk_fma_f32 v[174:175], v[246:247], v[136:137], v[174:175] op_sel:[0,1,0]
	v_pk_fma_f32 v[172:173], v[248:249], v[138:139], v[172:173] op_sel_hi:[1,0,1]
	v_pk_fma_f32 v[174:175], v[250:251], v[138:139], v[174:175] op_sel:[0,1,0]
	ds_read_b128 v[132:135], v252 offset:9024
	ds_read_b128 v[136:139], v252 offset:9104
	v_pk_add_f32 v[172:173], v[172:173], v[174:175]
	ds_write_b64 v254, v[172:173] offset:12288
	s_waitcnt lgkmcnt(10)
	v_pk_mul_f32 v[168:169], v[236:237], v[100:101] op_sel_hi:[1,0]
	v_pk_mul_f32 v[170:171], v[238:239], v[100:101] op_sel:[0,1]
	v_pk_fma_f32 v[168:169], v[240:241], v[102:103], v[168:169] op_sel_hi:[1,0,1]
	v_pk_fma_f32 v[170:171], v[242:243], v[102:103], v[170:171] op_sel:[0,1,0]
	v_pk_fma_f32 v[168:169], v[244:245], v[104:105], v[168:169] op_sel_hi:[1,0,1]
	v_pk_fma_f32 v[170:171], v[246:247], v[104:105], v[170:171] op_sel:[0,1,0]
	v_pk_fma_f32 v[168:169], v[248:249], v[106:107], v[168:169] op_sel_hi:[1,0,1]
	v_pk_fma_f32 v[170:171], v[250:251], v[106:107], v[170:171] op_sel:[0,1,0]
	ds_read_b128 v[100:103], v252 offset:10256
	ds_read_b128 v[104:107], v252 offset:10336
	v_pk_add_f32 v[168:169], v[168:169], v[170:171]
	s_waitcnt lgkmcnt(10)
	v_pk_mul_f32 v[236:237], v[236:237], v[108:109] op_sel_hi:[1,0]
	v_pk_mul_f32 v[238:239], v[238:239], v[108:109] op_sel:[0,1]
	v_pk_mul_f32 v[240:241], v[240:241], v[110:111] op_sel_hi:[1,0]
	v_pk_mul_f32 v[242:243], v[242:243], v[110:111] op_sel:[0,1]
	v_pk_mul_f32 v[244:245], v[244:245], v[112:113] op_sel_hi:[1,0]
	v_pk_mul_f32 v[246:247], v[246:247], v[112:113] op_sel:[0,1]
	v_pk_mul_f32 v[248:249], v[248:249], v[114:115] op_sel_hi:[1,0]
	v_pk_mul_f32 v[250:251], v[250:251], v[114:115] op_sel:[0,1]
	v_add_f32_dpp v168, v168, v168 quad_perm:[1,0,3,2] row_mask:0xf bank_mask:0xf bound_ctrl:1
	v_add_f32_dpp v169, v169, v169 quad_perm:[1,0,3,2] row_mask:0xf bank_mask:0xf bound_ctrl:1
	ds_read_b128 v[108:111], v252 offset:10240
	v_add_f32_dpp v168, v168, v168 quad_perm:[2,3,0,1] row_mask:0xf bank_mask:0xf bound_ctrl:1
	v_add_f32_dpp v169, v169, v169 quad_perm:[2,3,0,1] row_mask:0xf bank_mask:0xf bound_ctrl:1
	ds_read_b128 v[112:115], v252 offset:10320
	v_add_f32_dpp v168, v168, v168 row_half_mirror row_mask:0xf bank_mask:0xf bound_ctrl:1
	v_add_f32_dpp v169, v169, v169 row_half_mirror row_mask:0xf bank_mask:0xf bound_ctrl:1
	s_waitcnt lgkmcnt(10)
	v_pk_fma_f32 v[236:237], v[168:169], v[116:117], v[236:237] op_sel_hi:[1,0,1]
	v_pk_fma_f32 v[238:239], v[168:169], v[116:117], v[238:239] op_sel:[0,1,0]
	v_pk_fma_f32 v[240:241], v[168:169], v[118:119], v[240:241] op_sel_hi:[1,0,1]
	v_pk_fma_f32 v[242:243], v[168:169], v[118:119], v[242:243] op_sel:[0,1,0]
	v_pk_fma_f32 v[244:245], v[168:169], v[120:121], v[244:245] op_sel_hi:[1,0,1]
	v_pk_fma_f32 v[246:247], v[168:169], v[120:121], v[246:247] op_sel:[0,1,0]
	v_pk_fma_f32 v[248:249], v[168:169], v[122:123], v[248:249] op_sel_hi:[1,0,1]
	v_pk_fma_f32 v[250:251], v[168:169], v[122:123], v[250:251] op_sel:[0,1,0]
	ds_read_b128 v[116:119], v252 offset:10272
	ds_read_b128 v[120:123], v252 offset:10352
	s_waitcnt lgkmcnt(9)
	v_pk_fma_f32 v[236:237], v[166:167], v[124:125], v[236:237] op_sel_hi:[1,0,1]
	v_pk_fma_f32 v[238:239], v[166:167], v[124:125], v[238:239] op_sel:[0,1,0]
	v_pk_fma_f32 v[240:241], v[166:167], v[126:127], v[240:241] op_sel_hi:[1,0,1]
	v_pk_fma_f32 v[242:243], v[166:167], v[126:127], v[242:243] op_sel:[0,1,0]
	v_pk_fma_f32 v[244:245], v[166:167], v[128:129], v[244:245] op_sel_hi:[1,0,1]
	v_pk_fma_f32 v[246:247], v[166:167], v[128:129], v[246:247] op_sel:[0,1,0]
	v_pk_fma_f32 v[248:249], v[166:167], v[130:131], v[248:249] op_sel_hi:[1,0,1]
	v_pk_fma_f32 v[250:251], v[166:167], v[130:131], v[250:251] op_sel:[0,1,0]
	ds_read_b128 v[124:127], v252 offset:10288
	ds_read_b128 v[128:131], v252 offset:10368
	ds_read_b64 v[166:167], v253 offset:2048
	s_waitcnt lgkmcnt(10)
	v_pk_mul_f32 v[172:173], v[236:237], v[132:133] op_sel_hi:[1,0]
	v_pk_mul_f32 v[174:175], v[238:239], v[132:133] op_sel:[0,1]
	v_pk_fma_f32 v[172:173], v[240:241], v[134:135], v[172:173] op_sel_hi:[1,0,1]
	v_pk_fma_f32 v[174:175], v[242:243], v[134:135], v[174:175] op_sel:[0,1,0]
	v_pk_fma_f32 v[172:173], v[244:245], v[136:137], v[172:173] op_sel_hi:[1,0,1]
	v_pk_fma_f32 v[174:175], v[246:247], v[136:137], v[174:175] op_sel:[0,1,0]
	v_pk_fma_f32 v[172:173], v[248:249], v[138:139], v[172:173] op_sel_hi:[1,0,1]
	v_pk_fma_f32 v[174:175], v[250:251], v[138:139], v[174:175] op_sel:[0,1,0]
	ds_read_b128 v[132:135], v252 offset:10304
	ds_read_b128 v[136:139], v252 offset:10384
	v_pk_add_f32 v[172:173], v[172:173], v[174:175]
	ds_write_b64 v254, v[172:173] offset:14336
	s_waitcnt lgkmcnt(10)
	v_pk_mul_f32 v[168:169], v[236:237], v[100:101] op_sel_hi:[1,0]
	v_pk_mul_f32 v[170:171], v[238:239], v[100:101] op_sel:[0,1]
	v_pk_fma_f32 v[168:169], v[240:241], v[102:103], v[168:169] op_sel_hi:[1,0,1]
	v_pk_fma_f32 v[170:171], v[242:243], v[102:103], v[170:171] op_sel:[0,1,0]
	v_pk_fma_f32 v[168:169], v[244:245], v[104:105], v[168:169] op_sel_hi:[1,0,1]
	v_pk_fma_f32 v[170:171], v[246:247], v[104:105], v[170:171] op_sel:[0,1,0]
	v_pk_fma_f32 v[168:169], v[248:249], v[106:107], v[168:169] op_sel_hi:[1,0,1]
	v_pk_fma_f32 v[170:171], v[250:251], v[106:107], v[170:171] op_sel:[0,1,0]
	ds_read_b128 v[100:103], v252 offset:11536
	ds_read_b128 v[104:107], v252 offset:11616
	v_pk_add_f32 v[168:169], v[168:169], v[170:171]
	s_waitcnt lgkmcnt(10)
; #define LAS __attribute__((address_space(3)))
; template <int CTRL> __device__ __forceinline__ float dppf(float v) { return __builtin_bit_cast(float, __builtin_amdgcn_update_dpp(0, __builtin_bit_cast(int, v), CTRL, 0xF, 0xF, true)); }
; #define LO2(v) __builtin_shufflevector(v, v, 0, 1)
; #define HI2(v) __builtin_shufflevector(v, v, 2, 3)
; __device__ __forceinline__ void phase_scan(const Args& a, LAS unsigned char* lds) {
;     ...
;                 for (int s = 0; s < TC; ++s) {
;                     const LAS float* o = obase + (s + 1) * 320;
;                     const f32x4 now = *(const LAS f32x4*)(o), noa = *(const LAS f32x4*)(o + 4), nob = *(const LAS f32x4*)(o + 8), nok = *(const LAS f32x4*)(o + 12), norr = *(const LAS f32x4*)(o + 16);
;                     const f32x2 nvv = *(const LAS f32x2*)(vbase + (s + 1) * 64);
;                     const f32x2 p = pkfma_b<1>(C3, HI2(oa), pkfma_b<0>(C2, HI2(oa), pkfma_b<1>(C1, LO2(oa), pkmul_b<0>(C0, LO2(oa)))));
;                     float sa0 = p.x, sa1 = p.y;
;                     sa0 = reduce16(sa0); asm volatile("" : "+v"(sa0)); sa1 = reduce16(sa1);
;                     const f32x2 sap = {sa0, sa1};
;                     C0 = pkfma_b<0>(vv, LO2(ok), pkfma_b<0>(sap, LO2(ob), pkmul_b<0>(C0, LO2(ow))));
;                     C1 = pkfma_b<1>(vv, LO2(ok), pkfma_b<1>(sap, LO2(ob), pkmul_b<1>(C1, LO2(ow))));
;                     C2 = pkfma_b<0>(vv, HI2(ok), pkfma_b<0>(sap, HI2(ob), pkmul_b<0>(C2, HI2(ow))));
;                     C3 = pkfma_b<1>(vv, HI2(ok), pkfma_b<1>(sap, HI2(ob), pkmul_b<1>(C3, HI2(ow))));
;                     const f32x2 q = pkfma_b<1>(C3, HI2(orr), pkfma_b<0>(C2, HI2(orr), pkfma_b<1>(C1, LO2(orr), pkmul_b<0>(C0, LO2(orr)))));
;                     float y0 = q.x, y1 = q.y;
;                     y0 += dppf<0xB1>(y0); y1 += dppf<0xB1>(y1);
;                     *(LAS f32x2*)(yb + ((s * 32 + (r0 >> 1)) * 8 + ((lane >> 1) & 7)) * 2) = (f32x2){y0, y1};
;                     ow = now; oa = noa; ob = nob; ok = nok; orr = norr; vv = nvv;
;                 }
	v_pk_mul_f32 v[236:237], v[236:237], v[108:109] op_sel_hi:[1,0]
	v_pk_mul_f32 v[238:239], v[238:239], v[108:109] op_sel:[0,1]
	v_pk_mul_f32 v[240:241], v[240:241], v[110:111] op_sel_hi:[1,0]
	v_pk_mul_f32 v[242:243], v[242:243], v[110:111] op_sel:[0,1]
	v_pk_mul_f32 v[244:245], v[244:245], v[112:113] op_sel_hi:[1,0]
	v_pk_mul_f32 v[246:247], v[246:247], v[112:113] op_sel:[0,1]
	v_pk_mul_f32 v[248:249], v[248:249], v[114:115] op_sel_hi:[1,0]
	v_pk_mul_f32 v[250:251], v[250:251], v[114:115] op_sel:[0,1]
	v_add_f32_dpp v168, v168, v168 quad_perm:[1,0,3,2] row_mask:0xf bank_mask:0xf bound_ctrl:1
	v_add_f32_dpp v169, v169, v169 quad_perm:[1,0,3,2] row_mask:0xf bank_mask:0xf bound_ctrl:1
	ds_read_b128 v[108:111], v252 offset:11520
	v_add_f32_dpp v168, v168, v168 quad_perm:[2,3,0,1] row_mask:0xf bank_mask:0xf bound_ctrl:1
	v_add_f32_dpp v169, v169, v169 quad_perm:[2,3,0,1] row_mask:0xf bank_mask:0xf bound_ctrl:1
	ds_read_b128 v[112:115], v252 offset:11600
	v_add_f32_dpp v168, v168, v168 row_half_mirror row_mask:0xf bank_mask:0xf bound_ctrl:1
	v_add_f32_dpp v169, v169, v169 row_half_mirror row_mask:0xf bank_mask:0xf bound_ctrl:1
	s_waitcnt lgkmcnt(10)
	v_pk_fma_f32 v[236:237], v[168:169], v[116:117], v[236:237] op_sel_hi:[1,0,1]
	v_pk_fma_f32 v[238:239], v[168:169], v[116:117], v[238:239] op_sel:[0,1,0]
	v_pk_fma_f32 v[240:241], v[168:169], v[118:119], v[240:241] op_sel_hi:[1,0,1]
	v_pk_fma_f32 v[242:243], v[168:169], v[118:119], v[242:243] op_sel:[0,1,0]
	v_pk_fma_f32 v[244:245], v[168:169], v[120:121], v[244:245] op_sel_hi:[1,0,1]
	v_pk_fma_f32 v[246:247], v[168:169], v[120:121], v[246:247] op_sel:[0,1,0]
	v_pk_fma_f32 v[248:249], v[168:169], v[122:123], v[248:249] op_sel_hi:[1,0,1]
	v_pk_fma_f32 v[250:251], v[168:169], v[122:123], v[250:251] op_sel:[0,1,0]
	ds_read_b128 v[116:119], v252 offset:11552
	ds_read_b128 v[120:123], v252 offset:11632
	s_waitcnt lgkmcnt(9)
	v_pk_fma_f32 v[236:237], v[166:167], v[124:125], v[236:237] op_sel_hi:[1,0,1]
	v_pk_fma_f32 v[238:239], v[166:167], v[124:125], v[238:239] op_sel:[0,1,0]
	v_pk_fma_f32 v[240:241], v[166:167], v[126:127], v[240:241] op_sel_hi:[1,0,1]
	v_pk_fma_f32 v[242:243], v[166:167], v[126:127], v[242:243] op_sel:[0,1,0]
	v_pk_fma_f32 v[244:245], v[166:167], v[128:129], v[244:245] op_sel_hi:[1,0,1]
	v_pk_fma_f32 v[246:247], v[166:167], v[128:129], v[246:247] op_sel:[0,1,0]
	v_pk_fma_f32 v[248:249], v[166:167], v[130:131], v[248:249] op_sel_hi:[1,0,1]
	v_pk_fma_f32 v[250:251], v[166:167], v[130:131], v[250:251] op_sel:[0,1,0]
	ds_read_b128 v[124:127], v252 offset:11568
	ds_read_b128 v[128:131], v252 offset:11648
	ds_read_b64 v[166:167], v253 offset:2304
	s_waitcnt lgkmcnt(10)
	v_pk_mul_f32 v[172:173], v[236:237], v[132:133] op_sel_hi:[1,0]
	v_pk_mul_f32 v[174:175], v[238:239], v[132:133] op_sel:[0,1]
	v_pk_fma_f32 v[172:173], v[240:241], v[134:135], v[172:173] op_sel_hi:[1,0,1]
	v_pk_fma_f32 v[174:175], v[242:243], v[134:135], v[174:175] op_sel:[0,1,0]
	v_pk_fma_f32 v[172:173], v[244:245], v[136:137], v[172:173] op_sel_hi:[1,0,1]
	v_pk_fma_f32 v[174:175], v[246:247], v[136:137], v[174:175] op_sel:[0,1,0]
	v_pk_fma_f32 v[172:173], v[248:249], v[138:139], v[172:173] op_sel_hi:[1,0,1]
	v_pk_fma_f32 v[174:175], v[250:251], v[138:139], v[174:175] op_sel:[0,1,0]
	ds_read_b128 v[132:135], v252 offset:11584
	ds_read_b128 v[136:139], v252 offset:11664
	v_pk_add_f32 v[172:173], v[172:173], v[174:175]
	ds_write_b64 v254, v[172:173] offset:16384
	s_waitcnt lgkmcnt(10)
	v_pk_mul_f32 v[168:169], v[236:237], v[100:101] op_sel_hi:[1,0]
	v_pk_mul_f32 v[170:171], v[238:239], v[100:101] op_sel:[0,1]
	v_pk_fma_f32 v[168:169], v[240:241], v[102:103], v[168:169] op_sel_hi:[1,0,1]
	v_pk_fma_f32 v[170:171], v[242:243], v[102:103], v[170:171] op_sel:[0,1,0]
	v_pk_fma_f32 v[168:169], v[244:245], v[104:105], v[168:169] op_sel_hi:[1,0,1]
	v_pk_fma_f32 v[170:171], v[246:247], v[104:105], v[170:171] op_sel:[0,1,0]
	v_pk_fma_f32 v[168:169], v[248:249], v[106:107], v[168:169] op_sel_hi:[1,0,1]
	v_pk_fma_f32 v[170:171], v[250:251], v[106:107], v[170:171] op_sel:[0,1,0]
	ds_read_b128 v[100:103], v252 offset:12816
	ds_read_b128 v[104:107], v252 offset:12896
	v_pk_add_f32 v[168:169], v[168:169], v[170:171]
	s_waitcnt lgkmcnt(10)
	v_pk_mul_f32 v[236:237], v[236:237], v[108:109] op_sel_hi:[1,0]
	v_pk_mul_f32 v[238:239], v[238:239], v[108:109] op_sel:[0,1]
	v_pk_mul_f32 v[240:241], v[240:241], v[110:111] op_sel_hi:[1,0]
	v_pk_mul_f32 v[242:243], v[242:243], v[110:111] op_sel:[0,1]
	v_pk_mul_f32 v[244:245], v[244:245], v[112:113] op_sel_hi:[1,0]
	v_pk_mul_f32 v[246:247], v[246:247], v[112:113] op_sel:[0,1]
	v_pk_mul_f32 v[248:249], v[248:249], v[114:115] op_sel_hi:[1,0]
	v_pk_mul_f32 v[250:251], v[250:251], v[114:115] op_sel:[0,1]
	v_add_f32_dpp v168, v168, v168 quad_perm:[1,0,3,2] row_mask:0xf bank_mask:0xf bound_ctrl:1
	v_add_f32_dpp v169, v169, v169 quad_perm:[1,0,3,2] row_mask:0xf bank_mask:0xf bound_ctrl:1
	ds_read_b128 v[108:111], v252 offset:12800
	v_add_f32_dpp v168, v168, v168 quad_perm:[2,3,0,1] row_mask:0xf bank_mask:0xf bound_ctrl:1
	v_add_f32_dpp v169, v169, v169 quad_perm:[2,3,0,1] row_mask:0xf bank_mask:0xf bound_ctrl:1
	ds_read_b128 v[112:115], v252 offset:12880
	v_add_f32_dpp v168, v168, v168 row_half_mirror row_mask:0xf bank_mask:0xf bound_ctrl:1
	v_add_f32_dpp v169, v169, v169 row_half_mirror row_mask:0xf bank_mask:0xf bound_ctrl:1
	s_waitcnt lgkmcnt(10)
; #define LAS __attribute__((address_space(3)))
; template <int CTRL> __device__ __forceinline__ float dppf(float v) { return __builtin_bit_cast(float, __builtin_amdgcn_update_dpp(0, __builtin_bit_cast(int, v), CTRL, 0xF, 0xF, true)); }
; #define LO2(v) __builtin_shufflevector(v, v, 0, 1)
; #define HI2(v) __builtin_shufflevector(v, v, 2, 3)
; __device__ __forceinline__ void phase_scan(const Args& a, LAS unsigned char* lds) {
;     ...
;                 for (int s = 0; s < TC; ++s) {
;                     const LAS float* o = obase + (s + 1) * 320;
;                     const f32x4 now = *(const LAS f32x4*)(o), noa = *(const LAS f32x4*)(o + 4), nob = *(const LAS f32x4*)(o + 8), nok = *(const LAS f32x4*)(o + 12), norr = *(const LAS f32x4*)(o + 16);
;                     const f32x2 nvv = *(const LAS f32x2*)(vbase + (s + 1) * 64);
;                     const f32x2 p = pkfma_b<1>(C3, HI2(oa), pkfma_b<0>(C2, HI2(oa), pkfma_b<1>(C1, LO2(oa), pkmul_b<0>(C0, LO2(oa)))));
;                     float sa0 = p.x, sa1 = p.y;
;                     sa0 = reduce16(sa0); asm volatile("" : "+v"(sa0)); sa1 = reduce16(sa1);
;                     const f32x2 sap = {sa0, sa1};
;                     C0 = pkfma_b<0>(vv, LO2(ok), pkfma_b<0>(sap, LO2(ob), pkmul_b<0>(C0, LO2(ow))));
;                     C1 = pkfma_b<1>(vv, LO2(ok), pkfma_b<1>(sap, LO2(ob), pkmul_b<1>(C1, LO2(ow))));
;                     C2 = pkfma_b<0>(vv, HI2(ok), pkfma_b<0>(sap, HI2(ob), pkmul_b<0>(C2, HI2(ow))));
;                     C3 = pkfma_b<1>(vv, HI2(ok), pkfma_b<1>(sap, HI2(ob), pkmul_b<1>(C3, HI2(ow))));
;                     const f32x2 q = pkfma_b<1>(C3, HI2(orr), pkfma_b<0>(C2, HI2(orr), pkfma_b<1>(C1, LO2(orr), pkmul_b<0>(C0, LO2(orr)))));
;                     float y0 = q.x, y1 = q.y;
;                     y0 += dppf<0xB1>(y0); y1 += dppf<0xB1>(y1);
;                     *(LAS f32x2*)(yb + ((s * 32 + (r0 >> 1)) * 8 + ((lane >> 1) & 7)) * 2) = (f32x2){y0, y1};
;                     ow = now; oa = noa; ob = nob; ok = nok; orr = norr; vv = nvv;
;                 }
	v_pk_fma_f32 v[236:237], v[168:169], v[116:117], v[236:237] op_sel_hi:[1,0,1]
	v_pk_fma_f32 v[238:239], v[168:169], v[116:117], v[238:239] op_sel:[0,1,0]
	v_pk_fma_f32 v[240:241], v[168:169], v[118:119], v[240:241] op_sel_hi:[1,0,1]
	v_pk_fma_f32 v[242:243], v[168:169], v[118:119], v[242:243] op_sel:[0,1,0]
	v_pk_fma_f32 v[244:245], v[168:169], v[120:121], v[244:245] op_sel_hi:[1,0,1]
	v_pk_fma_f32 v[246:247], v[168:169], v[120:121], v[246:247] op_sel:[0,1,0]
	v_pk_fma_f32 v[248:249], v[168:169], v[122:123], v[248:249] op_sel_hi:[1,0,1]
	v_pk_fma_f32 v[250:251], v[168:169], v[122:123], v[250:251] op_sel:[0,1,0]
	ds_read_b128 v[116:119], v252 offset:12832
	ds_read_b128 v[120:123], v252 offset:12912
	s_waitcnt lgkmcnt(9)
	v_pk_fma_f32 v[236:237], v[166:167], v[124:125], v[236:237] op_sel_hi:[1,0,1]
	v_pk_fma_f32 v[238:239], v[166:167], v[124:125], v[238:239] op_sel:[0,1,0]
	v_pk_fma_f32 v[240:241], v[166:167], v[126:127], v[240:241] op_sel_hi:[1,0,1]
	v_pk_fma_f32 v[242:243], v[166:167], v[126:127], v[242:243] op_sel:[0,1,0]
	v_pk_fma_f32 v[244:245], v[166:167], v[128:129], v[244:245] op_sel_hi:[1,0,1]
	v_pk_fma_f32 v[246:247], v[166:167], v[128:129], v[246:247] op_sel:[0,1,0]
	v_pk_fma_f32 v[248:249], v[166:167], v[130:131], v[248:249] op_sel_hi:[1,0,1]
	v_pk_fma_f32 v[250:251], v[166:167], v[130:131], v[250:251] op_sel:[0,1,0]
	ds_read_b128 v[124:127], v252 offset:12848
	ds_read_b128 v[128:131], v252 offset:12928
	ds_read_b64 v[166:167], v253 offset:2560
	s_waitcnt lgkmcnt(10)
	v_pk_mul_f32 v[172:173], v[236:237], v[132:133] op_sel_hi:[1,0]
	v_pk_mul_f32 v[174:175], v[238:239], v[132:133] op_sel:[0,1]
	v_pk_fma_f32 v[172:173], v[240:241], v[134:135], v[172:173] op_sel_hi:[1,0,1]
	v_pk_fma_f32 v[174:175], v[242:243], v[134:135], v[174:175] op_sel:[0,1,0]
	v_pk_fma_f32 v[172:173], v[244:245], v[136:137], v[172:173] op_sel_hi:[1,0,1]
	v_pk_fma_f32 v[174:175], v[246:247], v[136:137], v[174:175] op_sel:[0,1,0]
	v_pk_fma_f32 v[172:173], v[248:249], v[138:139], v[172:173] op_sel_hi:[1,0,1]
	v_pk_fma_f32 v[174:175], v[250:251], v[138:139], v[174:175] op_sel:[0,1,0]
	ds_read_b128 v[132:135], v252 offset:12864
	ds_read_b128 v[136:139], v252 offset:12944
	v_pk_add_f32 v[172:173], v[172:173], v[174:175]
	ds_write_b64 v254, v[172:173] offset:18432
	s_waitcnt lgkmcnt(10)
	v_pk_mul_f32 v[168:169], v[236:237], v[100:101] op_sel_hi:[1,0]
	v_pk_mul_f32 v[170:171], v[238:239], v[100:101] op_sel:[0,1]
	v_pk_fma_f32 v[168:169], v[240:241], v[102:103], v[168:169] op_sel_hi:[1,0,1]
	v_pk_fma_f32 v[170:171], v[242:243], v[102:103], v[170:171] op_sel:[0,1,0]
	v_pk_fma_f32 v[168:169], v[244:245], v[104:105], v[168:169] op_sel_hi:[1,0,1]
	v_pk_fma_f32 v[170:171], v[246:247], v[104:105], v[170:171] op_sel:[0,1,0]
	v_pk_fma_f32 v[168:169], v[248:249], v[106:107], v[168:169] op_sel_hi:[1,0,1]
	v_pk_fma_f32 v[170:171], v[250:251], v[106:107], v[170:171] op_sel:[0,1,0]
	ds_read_b128 v[100:103], v252 offset:14096
	ds_read_b128 v[104:107], v252 offset:14176
	v_pk_add_f32 v[168:169], v[168:169], v[170:171]
	s_waitcnt lgkmcnt(10)
	v_pk_mul_f32 v[236:237], v[236:237], v[108:109] op_sel_hi:[1,0]
	v_pk_mul_f32 v[238:239], v[238:239], v[108:109] op_sel:[0,1]
	v_pk_mul_f32 v[240:241], v[240:241], v[110:111] op_sel_hi:[1,0]
	v_pk_mul_f32 v[242:243], v[242:243], v[110:111] op_sel:[0,1]
	v_pk_mul_f32 v[244:245], v[244:245], v[112:113] op_sel_hi:[1,0]
	v_pk_mul_f32 v[246:247], v[246:247], v[112:113] op_sel:[0,1]
	v_pk_mul_f32 v[248:249], v[248:249], v[114:115] op_sel_hi:[1,0]
	v_pk_mul_f32 v[250:251], v[250:251], v[114:115] op_sel:[0,1]
	v_add_f32_dpp v168, v168, v168 quad_perm:[1,0,3,2] row_mask:0xf bank_mask:0xf bound_ctrl:1
	v_add_f32_dpp v169, v169, v169 quad_perm:[1,0,3,2] row_mask:0xf bank_mask:0xf bound_ctrl:1
	ds_read_b128 v[108:111], v252 offset:14080
	v_add_f32_dpp v168, v168, v168 quad_perm:[2,3,0,1] row_mask:0xf bank_mask:0xf bound_ctrl:1
	v_add_f32_dpp v169, v169, v169 quad_perm:[2,3,0,1] row_mask:0xf bank_mask:0xf bound_ctrl:1
	ds_read_b128 v[112:115], v252 offset:14160
	v_add_f32_dpp v168, v168, v168 row_half_mirror row_mask:0xf bank_mask:0xf bound_ctrl:1
	v_add_f32_dpp v169, v169, v169 row_half_mirror row_mask:0xf bank_mask:0xf bound_ctrl:1
	s_waitcnt lgkmcnt(10)
	v_pk_fma_f32 v[236:237], v[168:169], v[116:117], v[236:237] op_sel_hi:[1,0,1]
	v_pk_fma_f32 v[238:239], v[168:169], v[116:117], v[238:239] op_sel:[0,1,0]
	v_pk_fma_f32 v[240:241], v[168:169], v[118:119], v[240:241] op_sel_hi:[1,0,1]
	v_pk_fma_f32 v[242:243], v[168:169], v[118:119], v[242:243] op_sel:[0,1,0]
	v_pk_fma_f32 v[244:245], v[168:169], v[120:121], v[244:245] op_sel_hi:[1,0,1]
	v_pk_fma_f32 v[246:247], v[168:169], v[120:121], v[246:247] op_sel:[0,1,0]
	v_pk_fma_f32 v[248:249], v[168:169], v[122:123], v[248:249] op_sel_hi:[1,0,1]
	v_pk_fma_f32 v[250:251], v[168:169], v[122:123], v[250:251] op_sel:[0,1,0]
	ds_read_b128 v[116:119], v252 offset:14112
	ds_read_b128 v[120:123], v252 offset:14192
	s_waitcnt lgkmcnt(9)
	v_pk_fma_f32 v[236:237], v[166:167], v[124:125], v[236:237] op_sel_hi:[1,0,1]
	v_pk_fma_f32 v[238:239], v[166:167], v[124:125], v[238:239] op_sel:[0,1,0]
	v_pk_fma_f32 v[240:241], v[166:167], v[126:127], v[240:241] op_sel_hi:[1,0,1]
	v_pk_fma_f32 v[242:243], v[166:167], v[126:127], v[242:243] op_sel:[0,1,0]
	v_pk_fma_f32 v[244:245], v[166:167], v[128:129], v[244:245] op_sel_hi:[1,0,1]
	v_pk_fma_f32 v[246:247], v[166:167], v[128:129], v[246:247] op_sel:[0,1,0]
	v_pk_fma_f32 v[248:249], v[166:167], v[130:131], v[248:249] op_sel_hi:[1,0,1]
	v_pk_fma_f32 v[250:251], v[166:167], v[130:131], v[250:251] op_sel:[0,1,0]
	ds_read_b128 v[124:127], v252 offset:14128
	ds_read_b128 v[128:131], v252 offset:14208
	ds_read_b64 v[166:167], v253 offset:2816
	s_waitcnt lgkmcnt(10)
; #define LAS __attribute__((address_space(3)))
; template <int CTRL> __device__ __forceinline__ float dppf(float v) { return __builtin_bit_cast(float, __builtin_amdgcn_update_dpp(0, __builtin_bit_cast(int, v), CTRL, 0xF, 0xF, true)); }
; #define LO2(v) __builtin_shufflevector(v, v, 0, 1)
; #define HI2(v) __builtin_shufflevector(v, v, 2, 3)
; __device__ __forceinline__ void phase_scan(const Args& a, LAS unsigned char* lds) {
;     ...
;                 for (int s = 0; s < TC; ++s) {
;                     const LAS float* o = obase + (s + 1) * 320;
;                     const f32x4 now = *(const LAS f32x4*)(o), noa = *(const LAS f32x4*)(o + 4), nob = *(const LAS f32x4*)(o + 8), nok = *(const LAS f32x4*)(o + 12), norr = *(const LAS f32x4*)(o + 16);
;                     const f32x2 nvv = *(const LAS f32x2*)(vbase + (s + 1) * 64);
;                     const f32x2 p = pkfma_b<1>(C3, HI2(oa), pkfma_b<0>(C2, HI2(oa), pkfma_b<1>(C1, LO2(oa), pkmul_b<0>(C0, LO2(oa)))));
;                     float sa0 = p.x, sa1 = p.y;
;                     sa0 = reduce16(sa0); asm volatile("" : "+v"(sa0)); sa1 = reduce16(sa1);
;                     const f32x2 sap = {sa0, sa1};
;                     C0 = pkfma_b<0>(vv, LO2(ok), pkfma_b<0>(sap, LO2(ob), pkmul_b<0>(C0, LO2(ow))));
;                     C1 = pkfma_b<1>(vv, LO2(ok), pkfma_b<1>(sap, LO2(ob), pkmul_b<1>(C1, LO2(ow))));
;                     C2 = pkfma_b<0>(vv, HI2(ok), pkfma_b<0>(sap, HI2(ob), pkmul_b<0>(C2, HI2(ow))));
;                     C3 = pkfma_b<1>(vv, HI2(ok), pkfma_b<1>(sap, HI2(ob), pkmul_b<1>(C3, HI2(ow))));
;                     const f32x2 q = pkfma_b<1>(C3, HI2(orr), pkfma_b<0>(C2, HI2(orr), pkfma_b<1>(C1, LO2(orr), pkmul_b<0>(C0, LO2(orr)))));
;                     float y0 = q.x, y1 = q.y;
;                     y0 += dppf<0xB1>(y0); y1 += dppf<0xB1>(y1);
;                     *(LAS f32x2*)(yb + ((s * 32 + (r0 >> 1)) * 8 + ((lane >> 1) & 7)) * 2) = (f32x2){y0, y1};
;                     ow = now; oa = noa; ob = nob; ok = nok; orr = norr; vv = nvv;
;                 }
	v_pk_mul_f32 v[172:173], v[236:237], v[132:133] op_sel_hi:[1,0]
	v_pk_mul_f32 v[174:175], v[238:239], v[132:133] op_sel:[0,1]
	v_pk_fma_f32 v[172:173], v[240:241], v[134:135], v[172:173] op_sel_hi:[1,0,1]
	v_pk_fma_f32 v[174:175], v[242:243], v[134:135], v[174:175] op_sel:[0,1,0]
	v_pk_fma_f32 v[172:173], v[244:245], v[136:137], v[172:173] op_sel_hi:[1,0,1]
	v_pk_fma_f32 v[174:175], v[246:247], v[136:137], v[174:175] op_sel:[0,1,0]
	v_pk_fma_f32 v[172:173], v[248:249], v[138:139], v[172:173] op_sel_hi:[1,0,1]
	v_pk_fma_f32 v[174:175], v[250:251], v[138:139], v[174:175] op_sel:[0,1,0]
	ds_read_b128 v[132:135], v252 offset:14144
	ds_read_b128 v[136:139], v252 offset:14224
	v_pk_add_f32 v[172:173], v[172:173], v[174:175]
	ds_write_b64 v254, v[172:173] offset:20480
	s_waitcnt lgkmcnt(10)
	v_pk_mul_f32 v[168:169], v[236:237], v[100:101] op_sel_hi:[1,0]
	v_pk_mul_f32 v[170:171], v[238:239], v[100:101] op_sel:[0,1]
	v_pk_fma_f32 v[168:169], v[240:241], v[102:103], v[168:169] op_sel_hi:[1,0,1]
	v_pk_fma_f32 v[170:171], v[242:243], v[102:103], v[170:171] op_sel:[0,1,0]
	v_pk_fma_f32 v[168:169], v[244:245], v[104:105], v[168:169] op_sel_hi:[1,0,1]
	v_pk_fma_f32 v[170:171], v[246:247], v[104:105], v[170:171] op_sel:[0,1,0]
	v_pk_fma_f32 v[168:169], v[248:249], v[106:107], v[168:169] op_sel_hi:[1,0,1]
	v_pk_fma_f32 v[170:171], v[250:251], v[106:107], v[170:171] op_sel:[0,1,0]
	ds_read_b128 v[100:103], v252 offset:15376
	ds_read_b128 v[104:107], v252 offset:15456
	v_pk_add_f32 v[168:169], v[168:169], v[170:171]
	s_waitcnt lgkmcnt(10)
	v_pk_mul_f32 v[236:237], v[236:237], v[108:109] op_sel_hi:[1,0]
	v_pk_mul_f32 v[238:239], v[238:239], v[108:109] op_sel:[0,1]
	v_pk_mul_f32 v[240:241], v[240:241], v[110:111] op_sel_hi:[1,0]
	v_pk_mul_f32 v[242:243], v[242:243], v[110:111] op_sel:[0,1]
	v_pk_mul_f32 v[244:245], v[244:245], v[112:113] op_sel_hi:[1,0]
	v_pk_mul_f32 v[246:247], v[246:247], v[112:113] op_sel:[0,1]
	v_pk_mul_f32 v[248:249], v[248:249], v[114:115] op_sel_hi:[1,0]
	v_pk_mul_f32 v[250:251], v[250:251], v[114:115] op_sel:[0,1]
	v_add_f32_dpp v168, v168, v168 quad_perm:[1,0,3,2] row_mask:0xf bank_mask:0xf bound_ctrl:1
	v_add_f32_dpp v169, v169, v169 quad_perm:[1,0,3,2] row_mask:0xf bank_mask:0xf bound_ctrl:1
	ds_read_b128 v[108:111], v252 offset:15360
	v_add_f32_dpp v168, v168, v168 quad_perm:[2,3,0,1] row_mask:0xf bank_mask:0xf bound_ctrl:1
	v_add_f32_dpp v169, v169, v169 quad_perm:[2,3,0,1] row_mask:0xf bank_mask:0xf bound_ctrl:1
	ds_read_b128 v[112:115], v252 offset:15440
	v_add_f32_dpp v168, v168, v168 row_half_mirror row_mask:0xf bank_mask:0xf bound_ctrl:1
	v_add_f32_dpp v169, v169, v169 row_half_mirror row_mask:0xf bank_mask:0xf bound_ctrl:1
	s_waitcnt lgkmcnt(10)
	v_pk_fma_f32 v[236:237], v[168:169], v[116:117], v[236:237] op_sel_hi:[1,0,1]
	v_pk_fma_f32 v[238:239], v[168:169], v[116:117], v[238:239] op_sel:[0,1,0]
	v_pk_fma_f32 v[240:241], v[168:169], v[118:119], v[240:241] op_sel_hi:[1,0,1]
	v_pk_fma_f32 v[242:243], v[168:169], v[118:119], v[242:243] op_sel:[0,1,0]
	v_pk_fma_f32 v[244:245], v[168:169], v[120:121], v[244:245] op_sel_hi:[1,0,1]
	v_pk_fma_f32 v[246:247], v[168:169], v[120:121], v[246:247] op_sel:[0,1,0]
	v_pk_fma_f32 v[248:249], v[168:169], v[122:123], v[248:249] op_sel_hi:[1,0,1]
	v_pk_fma_f32 v[250:251], v[168:169], v[122:123], v[250:251] op_sel:[0,1,0]
	ds_read_b128 v[116:119], v252 offset:15392
	ds_read_b128 v[120:123], v252 offset:15472
	s_waitcnt lgkmcnt(9)
	v_pk_fma_f32 v[236:237], v[166:167], v[124:125], v[236:237] op_sel_hi:[1,0,1]
	v_pk_fma_f32 v[238:239], v[166:167], v[124:125], v[238:239] op_sel:[0,1,0]
	v_pk_fma_f32 v[240:241], v[166:167], v[126:127], v[240:241] op_sel_hi:[1,0,1]
	v_pk_fma_f32 v[242:243], v[166:167], v[126:127], v[242:243] op_sel:[0,1,0]
	v_pk_fma_f32 v[244:245], v[166:167], v[128:129], v[244:245] op_sel_hi:[1,0,1]
	v_pk_fma_f32 v[246:247], v[166:167], v[128:129], v[246:247] op_sel:[0,1,0]
	v_pk_fma_f32 v[248:249], v[166:167], v[130:131], v[248:249] op_sel_hi:[1,0,1]
	v_pk_fma_f32 v[250:251], v[166:167], v[130:131], v[250:251] op_sel:[0,1,0]
	ds_read_b128 v[124:127], v252 offset:15408
	ds_read_b128 v[128:131], v252 offset:15488
	ds_read_b64 v[166:167], v253 offset:3072
	s_waitcnt lgkmcnt(10)
	v_pk_mul_f32 v[172:173], v[236:237], v[132:133] op_sel_hi:[1,0]
	v_pk_mul_f32 v[174:175], v[238:239], v[132:133] op_sel:[0,1]
	v_pk_fma_f32 v[172:173], v[240:241], v[134:135], v[172:173] op_sel_hi:[1,0,1]
	v_pk_fma_f32 v[174:175], v[242:243], v[134:135], v[174:175] op_sel:[0,1,0]
	v_pk_fma_f32 v[172:173], v[244:245], v[136:137], v[172:173] op_sel_hi:[1,0,1]
	v_pk_fma_f32 v[174:175], v[246:247], v[136:137], v[174:175] op_sel:[0,1,0]
	v_pk_fma_f32 v[172:173], v[248:249], v[138:139], v[172:173] op_sel_hi:[1,0,1]
	v_pk_fma_f32 v[174:175], v[250:251], v[138:139], v[174:175] op_sel:[0,1,0]
	ds_read_b128 v[132:135], v252 offset:15424
	ds_read_b128 v[136:139], v252 offset:15504
	v_pk_add_f32 v[172:173], v[172:173], v[174:175]
	ds_write_b64 v254, v[172:173] offset:22528
	s_barrier
; #define LAS __attribute__((address_space(3)))
; template <int CTRL> __device__ __forceinline__ float dppf(float v) { return __builtin_bit_cast(float, __builtin_amdgcn_update_dpp(0, __builtin_bit_cast(int, v), CTRL, 0xF, 0xF, true)); }
; #define LO2(v) __builtin_shufflevector(v, v, 0, 1)
; #define HI2(v) __builtin_shufflevector(v, v, 2, 3)
; __device__ __forceinline__ void phase_scan(const Args& a, LAS unsigned char* lds) {
;     ...
;                 for (int s = 0; s < TC; ++s) {
;                     const LAS float* o = obase + (s + 1) * 320;
;                     const f32x4 now = *(const LAS f32x4*)(o), noa = *(const LAS f32x4*)(o + 4), nob = *(const LAS f32x4*)(o + 8), nok = *(const LAS f32x4*)(o + 12), norr = *(const LAS f32x4*)(o + 16);
;                     const f32x2 nvv = *(const LAS f32x2*)(vbase + (s + 1) * 64);
;                     const f32x2 p = pkfma_b<1>(C3, HI2(oa), pkfma_b<0>(C2, HI2(oa), pkfma_b<1>(C1, LO2(oa), pkmul_b<0>(C0, LO2(oa)))));
;                     float sa0 = p.x, sa1 = p.y;
;                     sa0 = reduce16(sa0); asm volatile("" : "+v"(sa0)); sa1 = reduce16(sa1);
;                     const f32x2 sap = {sa0, sa1};
;                     C0 = pkfma_b<0>(vv, LO2(ok), pkfma_b<0>(sap, LO2(ob), pkmul_b<0>(C0, LO2(ow))));
;                     C1 = pkfma_b<1>(vv, LO2(ok), pkfma_b<1>(sap, LO2(ob), pkmul_b<1>(C1, LO2(ow))));
;                     C2 = pkfma_b<0>(vv, HI2(ok), pkfma_b<0>(sap, HI2(ob), pkmul_b<0>(C2, HI2(ow))));
;                     C3 = pkfma_b<1>(vv, HI2(ok), pkfma_b<1>(sap, HI2(ob), pkmul_b<1>(C3, HI2(ow))));
;                     const f32x2 q = pkfma_b<1>(C3, HI2(orr), pkfma_b<0>(C2, HI2(orr), pkfma_b<1>(C1, LO2(orr), pkmul_b<0>(C0, LO2(orr)))));
;                     float y0 = q.x, y1 = q.y;
;                     y0 += dppf<0xB1>(y0); y1 += dppf<0xB1>(y1);
;                     *(LAS f32x2*)(yb + ((s * 32 + (r0 >> 1)) * 8 + ((lane >> 1) & 7)) * 2) = (f32x2){y0, y1};
;                     ow = now; oa = noa; ob = nob; ok = nok; orr = norr; vv = nvv;
;                 }
	s_waitcnt lgkmcnt(10)
	v_pk_mul_f32 v[168:169], v[236:237], v[100:101] op_sel_hi:[1,0]
	v_pk_mul_f32 v[170:171], v[238:239], v[100:101] op_sel:[0,1]
	v_pk_fma_f32 v[168:169], v[240:241], v[102:103], v[168:169] op_sel_hi:[1,0,1]
	v_pk_fma_f32 v[170:171], v[242:243], v[102:103], v[170:171] op_sel:[0,1,0]
	v_pk_fma_f32 v[168:169], v[244:245], v[104:105], v[168:169] op_sel_hi:[1,0,1]
	v_pk_fma_f32 v[170:171], v[246:247], v[104:105], v[170:171] op_sel:[0,1,0]
	v_pk_fma_f32 v[168:169], v[248:249], v[106:107], v[168:169] op_sel_hi:[1,0,1]
	v_pk_fma_f32 v[170:171], v[250:251], v[106:107], v[170:171] op_sel:[0,1,0]
	ds_read_b128 v[100:103], v252 offset:16656
	ds_read_b128 v[104:107], v252 offset:16736
	v_pk_add_f32 v[168:169], v[168:169], v[170:171]
	s_waitcnt lgkmcnt(10)
	v_pk_mul_f32 v[236:237], v[236:237], v[108:109] op_sel_hi:[1,0]
	v_pk_mul_f32 v[238:239], v[238:239], v[108:109] op_sel:[0,1]
	v_pk_mul_f32 v[240:241], v[240:241], v[110:111] op_sel_hi:[1,0]
	v_pk_mul_f32 v[242:243], v[242:243], v[110:111] op_sel:[0,1]
	v_pk_mul_f32 v[244:245], v[244:245], v[112:113] op_sel_hi:[1,0]
	v_pk_mul_f32 v[246:247], v[246:247], v[112:113] op_sel:[0,1]
	v_pk_mul_f32 v[248:249], v[248:249], v[114:115] op_sel_hi:[1,0]
	v_pk_mul_f32 v[250:251], v[250:251], v[114:115] op_sel:[0,1]
	v_add_f32_dpp v168, v168, v168 quad_perm:[1,0,3,2] row_mask:0xf bank_mask:0xf bound_ctrl:1
	v_add_f32_dpp v169, v169, v169 quad_perm:[1,0,3,2] row_mask:0xf bank_mask:0xf bound_ctrl:1
	ds_read_b128 v[108:111], v252 offset:16640
	v_add_f32_dpp v168, v168, v168 quad_perm:[2,3,0,1] row_mask:0xf bank_mask:0xf bound_ctrl:1
	v_add_f32_dpp v169, v169, v169 quad_perm:[2,3,0,1] row_mask:0xf bank_mask:0xf bound_ctrl:1
	ds_read_b128 v[112:115], v252 offset:16720
	v_add_f32_dpp v168, v168, v168 row_half_mirror row_mask:0xf bank_mask:0xf bound_ctrl:1
	v_add_f32_dpp v169, v169, v169 row_half_mirror row_mask:0xf bank_mask:0xf bound_ctrl:1
	s_waitcnt lgkmcnt(10)
	v_pk_fma_f32 v[236:237], v[168:169], v[116:117], v[236:237] op_sel_hi:[1,0,1]
	v_pk_fma_f32 v[238:239], v[168:169], v[116:117], v[238:239] op_sel:[0,1,0]
	v_pk_fma_f32 v[240:241], v[168:169], v[118:119], v[240:241] op_sel_hi:[1,0,1]
	v_pk_fma_f32 v[242:243], v[168:169], v[118:119], v[242:243] op_sel:[0,1,0]
	v_pk_fma_f32 v[244:245], v[168:169], v[120:121], v[244:245] op_sel_hi:[1,0,1]
	v_pk_fma_f32 v[246:247], v[168:169], v[120:121], v[246:247] op_sel:[0,1,0]
	v_pk_fma_f32 v[248:249], v[168:169], v[122:123], v[248:249] op_sel_hi:[1,0,1]
	v_pk_fma_f32 v[250:251], v[168:169], v[122:123], v[250:251] op_sel:[0,1,0]
	ds_read_b128 v[116:119], v252 offset:16672
	ds_read_b128 v[120:123], v252 offset:16752
	s_waitcnt lgkmcnt(9)
	v_pk_fma_f32 v[236:237], v[166:167], v[124:125], v[236:237] op_sel_hi:[1,0,1]
	v_pk_fma_f32 v[238:239], v[166:167], v[124:125], v[238:239] op_sel:[0,1,0]
	v_pk_fma_f32 v[240:241], v[166:167], v[126:127], v[240:241] op_sel_hi:[1,0,1]
	v_pk_fma_f32 v[242:243], v[166:167], v[126:127], v[242:243] op_sel:[0,1,0]
	v_pk_fma_f32 v[244:245], v[166:167], v[128:129], v[244:245] op_sel_hi:[1,0,1]
	v_pk_fma_f32 v[246:247], v[166:167], v[128:129], v[246:247] op_sel:[0,1,0]
	v_pk_fma_f32 v[248:249], v[166:167], v[130:131], v[248:249] op_sel_hi:[1,0,1]
	v_pk_fma_f32 v[250:251], v[166:167], v[130:131], v[250:251] op_sel:[0,1,0]
	ds_read_b128 v[124:127], v252 offset:16688
	ds_read_b128 v[128:131], v252 offset:16768
	ds_read_b64 v[166:167], v253 offset:3328
	s_waitcnt lgkmcnt(10)
	v_pk_mul_f32 v[172:173], v[236:237], v[132:133] op_sel_hi:[1,0]
	v_pk_mul_f32 v[174:175], v[238:239], v[132:133] op_sel:[0,1]
	v_pk_fma_f32 v[172:173], v[240:241], v[134:135], v[172:173] op_sel_hi:[1,0,1]
	v_pk_fma_f32 v[174:175], v[242:243], v[134:135], v[174:175] op_sel:[0,1,0]
	v_pk_fma_f32 v[172:173], v[244:245], v[136:137], v[172:173] op_sel_hi:[1,0,1]
	v_pk_fma_f32 v[174:175], v[246:247], v[136:137], v[174:175] op_sel:[0,1,0]
	v_pk_fma_f32 v[172:173], v[248:249], v[138:139], v[172:173] op_sel_hi:[1,0,1]
	v_pk_fma_f32 v[174:175], v[250:251], v[138:139], v[174:175] op_sel:[0,1,0]
	ds_read_b128 v[132:135], v252 offset:16704
	ds_read_b128 v[136:139], v252 offset:16784
	v_pk_add_f32 v[172:173], v[172:173], v[174:175]
	ds_write_b64 v254, v[172:173] offset:24576
	s_waitcnt lgkmcnt(10)
	v_pk_mul_f32 v[168:169], v[236:237], v[100:101] op_sel_hi:[1,0]
	v_pk_mul_f32 v[170:171], v[238:239], v[100:101] op_sel:[0,1]
	v_pk_fma_f32 v[168:169], v[240:241], v[102:103], v[168:169] op_sel_hi:[1,0,1]
	v_pk_fma_f32 v[170:171], v[242:243], v[102:103], v[170:171] op_sel:[0,1,0]
	v_pk_fma_f32 v[168:169], v[244:245], v[104:105], v[168:169] op_sel_hi:[1,0,1]
	v_pk_fma_f32 v[170:171], v[246:247], v[104:105], v[170:171] op_sel:[0,1,0]
	v_pk_fma_f32 v[168:169], v[248:249], v[106:107], v[168:169] op_sel_hi:[1,0,1]
	v_pk_fma_f32 v[170:171], v[250:251], v[106:107], v[170:171] op_sel:[0,1,0]
	ds_read_b128 v[100:103], v252 offset:17936
	ds_read_b128 v[104:107], v252 offset:18016
	v_pk_add_f32 v[168:169], v[168:169], v[170:171]
	s_waitcnt lgkmcnt(10)
	v_pk_mul_f32 v[236:237], v[236:237], v[108:109] op_sel_hi:[1,0]
	v_pk_mul_f32 v[238:239], v[238:239], v[108:109] op_sel:[0,1]
	v_pk_mul_f32 v[240:241], v[240:241], v[110:111] op_sel_hi:[1,0]
	v_pk_mul_f32 v[242:243], v[242:243], v[110:111] op_sel:[0,1]
	v_pk_mul_f32 v[244:245], v[244:245], v[112:113] op_sel_hi:[1,0]
	v_pk_mul_f32 v[246:247], v[246:247], v[112:113] op_sel:[0,1]
	v_pk_mul_f32 v[248:249], v[248:249], v[114:115] op_sel_hi:[1,0]
	v_pk_mul_f32 v[250:251], v[250:251], v[114:115] op_sel:[0,1]
	v_add_f32_dpp v168, v168, v168 quad_perm:[1,0,3,2] row_mask:0xf bank_mask:0xf bound_ctrl:1
	v_add_f32_dpp v169, v169, v169 quad_perm:[1,0,3,2] row_mask:0xf bank_mask:0xf bound_ctrl:1
	ds_read_b128 v[108:111], v252 offset:17920
	v_add_f32_dpp v168, v168, v168 quad_perm:[2,3,0,1] row_mask:0xf bank_mask:0xf bound_ctrl:1
	v_add_f32_dpp v169, v169, v169 quad_perm:[2,3,0,1] row_mask:0xf bank_mask:0xf bound_ctrl:1
	ds_read_b128 v[112:115], v252 offset:18000
	v_add_f32_dpp v168, v168, v168 row_half_mirror row_mask:0xf bank_mask:0xf bound_ctrl:1
	v_add_f32_dpp v169, v169, v169 row_half_mirror row_mask:0xf bank_mask:0xf bound_ctrl:1
	s_waitcnt lgkmcnt(10)
; #define LAS __attribute__((address_space(3)))
; template <int CTRL> __device__ __forceinline__ float dppf(float v) { return __builtin_bit_cast(float, __builtin_amdgcn_update_dpp(0, __builtin_bit_cast(int, v), CTRL, 0xF, 0xF, true)); }
; #define LO2(v) __builtin_shufflevector(v, v, 0, 1)
; #define HI2(v) __builtin_shufflevector(v, v, 2, 3)
; __device__ __forceinline__ void phase_scan(const Args& a, LAS unsigned char* lds) {
;     ...
;                 for (int s = 0; s < TC; ++s) {
;                     const LAS float* o = obase + (s + 1) * 320;
;                     const f32x4 now = *(const LAS f32x4*)(o), noa = *(const LAS f32x4*)(o + 4), nob = *(const LAS f32x4*)(o + 8), nok = *(const LAS f32x4*)(o + 12), norr = *(const LAS f32x4*)(o + 16);
;                     const f32x2 nvv = *(const LAS f32x2*)(vbase + (s + 1) * 64);
;                     const f32x2 p = pkfma_b<1>(C3, HI2(oa), pkfma_b<0>(C2, HI2(oa), pkfma_b<1>(C1, LO2(oa), pkmul_b<0>(C0, LO2(oa)))));
;                     float sa0 = p.x, sa1 = p.y;
;                     sa0 = reduce16(sa0); asm volatile("" : "+v"(sa0)); sa1 = reduce16(sa1);
;                     const f32x2 sap = {sa0, sa1};
;                     C0 = pkfma_b<0>(vv, LO2(ok), pkfma_b<0>(sap, LO2(ob), pkmul_b<0>(C0, LO2(ow))));
;                     C1 = pkfma_b<1>(vv, LO2(ok), pkfma_b<1>(sap, LO2(ob), pkmul_b<1>(C1, LO2(ow))));
;                     C2 = pkfma_b<0>(vv, HI2(ok), pkfma_b<0>(sap, HI2(ob), pkmul_b<0>(C2, HI2(ow))));
;                     C3 = pkfma_b<1>(vv, HI2(ok), pkfma_b<1>(sap, HI2(ob), pkmul_b<1>(C3, HI2(ow))));
;                     const f32x2 q = pkfma_b<1>(C3, HI2(orr), pkfma_b<0>(C2, HI2(orr), pkfma_b<1>(C1, LO2(orr), pkmul_b<0>(C0, LO2(orr)))));
;                     float y0 = q.x, y1 = q.y;
;                     y0 += dppf<0xB1>(y0); y1 += dppf<0xB1>(y1);
;                     *(LAS f32x2*)(yb + ((s * 32 + (r0 >> 1)) * 8 + ((lane >> 1) & 7)) * 2) = (f32x2){y0, y1};
;                     ow = now; oa = noa; ob = nob; ok = nok; orr = norr; vv = nvv;
;                 }
	v_pk_fma_f32 v[236:237], v[168:169], v[116:117], v[236:237] op_sel_hi:[1,0,1]
	v_pk_fma_f32 v[238:239], v[168:169], v[116:117], v[238:239] op_sel:[0,1,0]
	v_pk_fma_f32 v[240:241], v[168:169], v[118:119], v[240:241] op_sel_hi:[1,0,1]
	v_pk_fma_f32 v[242:243], v[168:169], v[118:119], v[242:243] op_sel:[0,1,0]
	v_pk_fma_f32 v[244:245], v[168:169], v[120:121], v[244:245] op_sel_hi:[1,0,1]
	v_pk_fma_f32 v[246:247], v[168:169], v[120:121], v[246:247] op_sel:[0,1,0]
	v_pk_fma_f32 v[248:249], v[168:169], v[122:123], v[248:249] op_sel_hi:[1,0,1]
	v_pk_fma_f32 v[250:251], v[168:169], v[122:123], v[250:251] op_sel:[0,1,0]
	ds_read_b128 v[116:119], v252 offset:17952
	ds_read_b128 v[120:123], v252 offset:18032
	s_waitcnt lgkmcnt(9)
	v_pk_fma_f32 v[236:237], v[166:167], v[124:125], v[236:237] op_sel_hi:[1,0,1]
	v_pk_fma_f32 v[238:239], v[166:167], v[124:125], v[238:239] op_sel:[0,1,0]
	v_pk_fma_f32 v[240:241], v[166:167], v[126:127], v[240:241] op_sel_hi:[1,0,1]
	v_pk_fma_f32 v[242:243], v[166:167], v[126:127], v[242:243] op_sel:[0,1,0]
	v_pk_fma_f32 v[244:245], v[166:167], v[128:129], v[244:245] op_sel_hi:[1,0,1]
	v_pk_fma_f32 v[246:247], v[166:167], v[128:129], v[246:247] op_sel:[0,1,0]
	v_pk_fma_f32 v[248:249], v[166:167], v[130:131], v[248:249] op_sel_hi:[1,0,1]
	v_pk_fma_f32 v[250:251], v[166:167], v[130:131], v[250:251] op_sel:[0,1,0]
	ds_read_b128 v[124:127], v252 offset:17968
	ds_read_b128 v[128:131], v252 offset:18048
	ds_read_b64 v[166:167], v253 offset:3584
	s_waitcnt lgkmcnt(10)
	v_pk_mul_f32 v[172:173], v[236:237], v[132:133] op_sel_hi:[1,0]
	v_pk_mul_f32 v[174:175], v[238:239], v[132:133] op_sel:[0,1]
	v_pk_fma_f32 v[172:173], v[240:241], v[134:135], v[172:173] op_sel_hi:[1,0,1]
	v_pk_fma_f32 v[174:175], v[242:243], v[134:135], v[174:175] op_sel:[0,1,0]
	v_pk_fma_f32 v[172:173], v[244:245], v[136:137], v[172:173] op_sel_hi:[1,0,1]
	v_pk_fma_f32 v[174:175], v[246:247], v[136:137], v[174:175] op_sel:[0,1,0]
	v_pk_fma_f32 v[172:173], v[248:249], v[138:139], v[172:173] op_sel_hi:[1,0,1]
	v_pk_fma_f32 v[174:175], v[250:251], v[138:139], v[174:175] op_sel:[0,1,0]
	ds_read_b128 v[132:135], v252 offset:17984
	ds_read_b128 v[136:139], v252 offset:18064
	v_pk_add_f32 v[172:173], v[172:173], v[174:175]
	ds_write_b64 v254, v[172:173] offset:26624
	s_waitcnt lgkmcnt(10)
	v_pk_mul_f32 v[168:169], v[236:237], v[100:101] op_sel_hi:[1,0]
	v_pk_mul_f32 v[170:171], v[238:239], v[100:101] op_sel:[0,1]
	v_pk_fma_f32 v[168:169], v[240:241], v[102:103], v[168:169] op_sel_hi:[1,0,1]
	v_pk_fma_f32 v[170:171], v[242:243], v[102:103], v[170:171] op_sel:[0,1,0]
	v_pk_fma_f32 v[168:169], v[244:245], v[104:105], v[168:169] op_sel_hi:[1,0,1]
	v_pk_fma_f32 v[170:171], v[246:247], v[104:105], v[170:171] op_sel:[0,1,0]
	v_pk_fma_f32 v[168:169], v[248:249], v[106:107], v[168:169] op_sel_hi:[1,0,1]
	v_pk_fma_f32 v[170:171], v[250:251], v[106:107], v[170:171] op_sel:[0,1,0]
	ds_read_b128 v[100:103], v252 offset:19216
	ds_read_b128 v[104:107], v252 offset:19296
	v_pk_add_f32 v[168:169], v[168:169], v[170:171]
	s_waitcnt lgkmcnt(10)
	v_pk_mul_f32 v[236:237], v[236:237], v[108:109] op_sel_hi:[1,0]
	v_pk_mul_f32 v[238:239], v[238:239], v[108:109] op_sel:[0,1]
	v_pk_mul_f32 v[240:241], v[240:241], v[110:111] op_sel_hi:[1,0]
	v_pk_mul_f32 v[242:243], v[242:243], v[110:111] op_sel:[0,1]
	v_pk_mul_f32 v[244:245], v[244:245], v[112:113] op_sel_hi:[1,0]
	v_pk_mul_f32 v[246:247], v[246:247], v[112:113] op_sel:[0,1]
	v_pk_mul_f32 v[248:249], v[248:249], v[114:115] op_sel_hi:[1,0]
	v_pk_mul_f32 v[250:251], v[250:251], v[114:115] op_sel:[0,1]
	v_add_f32_dpp v168, v168, v168 quad_perm:[1,0,3,2] row_mask:0xf bank_mask:0xf bound_ctrl:1
	v_add_f32_dpp v169, v169, v169 quad_perm:[1,0,3,2] row_mask:0xf bank_mask:0xf bound_ctrl:1
	ds_read_b128 v[108:111], v252 offset:19200
	v_add_f32_dpp v168, v168, v168 quad_perm:[2,3,0,1] row_mask:0xf bank_mask:0xf bound_ctrl:1
	v_add_f32_dpp v169, v169, v169 quad_perm:[2,3,0,1] row_mask:0xf bank_mask:0xf bound_ctrl:1
	ds_read_b128 v[112:115], v252 offset:19280
	v_add_f32_dpp v168, v168, v168 row_half_mirror row_mask:0xf bank_mask:0xf bound_ctrl:1
	v_add_f32_dpp v169, v169, v169 row_half_mirror row_mask:0xf bank_mask:0xf bound_ctrl:1
	s_waitcnt lgkmcnt(10)
	v_pk_fma_f32 v[236:237], v[168:169], v[116:117], v[236:237] op_sel_hi:[1,0,1]
	v_pk_fma_f32 v[238:239], v[168:169], v[116:117], v[238:239] op_sel:[0,1,0]
	v_pk_fma_f32 v[240:241], v[168:169], v[118:119], v[240:241] op_sel_hi:[1,0,1]
	v_pk_fma_f32 v[242:243], v[168:169], v[118:119], v[242:243] op_sel:[0,1,0]
	v_pk_fma_f32 v[244:245], v[168:169], v[120:121], v[244:245] op_sel_hi:[1,0,1]
	v_pk_fma_f32 v[246:247], v[168:169], v[120:121], v[246:247] op_sel:[0,1,0]
	v_pk_fma_f32 v[248:249], v[168:169], v[122:123], v[248:249] op_sel_hi:[1,0,1]
	v_pk_fma_f32 v[250:251], v[168:169], v[122:123], v[250:251] op_sel:[0,1,0]
	ds_read_b128 v[116:119], v252 offset:19232
	ds_read_b128 v[120:123], v252 offset:19312
	s_waitcnt lgkmcnt(9)
	v_pk_fma_f32 v[236:237], v[166:167], v[124:125], v[236:237] op_sel_hi:[1,0,1]
	v_pk_fma_f32 v[238:239], v[166:167], v[124:125], v[238:239] op_sel:[0,1,0]
	v_pk_fma_f32 v[240:241], v[166:167], v[126:127], v[240:241] op_sel_hi:[1,0,1]
	v_pk_fma_f32 v[242:243], v[166:167], v[126:127], v[242:243] op_sel:[0,1,0]
	v_pk_fma_f32 v[244:245], v[166:167], v[128:129], v[244:245] op_sel_hi:[1,0,1]
	v_pk_fma_f32 v[246:247], v[166:167], v[128:129], v[246:247] op_sel:[0,1,0]
	v_pk_fma_f32 v[248:249], v[166:167], v[130:131], v[248:249] op_sel_hi:[1,0,1]
	v_pk_fma_f32 v[250:251], v[166:167], v[130:131], v[250:251] op_sel:[0,1,0]
	ds_read_b128 v[124:127], v252 offset:19248
	ds_read_b128 v[128:131], v252 offset:19328
	ds_read_b64 v[166:167], v253 offset:3840
	s_waitcnt lgkmcnt(10)
; #define LAS __attribute__((address_space(3)))
; template <int CTRL> __device__ __forceinline__ float dppf(float v) { return __builtin_bit_cast(float, __builtin_amdgcn_update_dpp(0, __builtin_bit_cast(int, v), CTRL, 0xF, 0xF, true)); }
; #define LO2(v) __builtin_shufflevector(v, v, 0, 1)
; #define HI2(v) __builtin_shufflevector(v, v, 2, 3)
; __device__ __forceinline__ void phase_scan(const Args& a, LAS unsigned char* lds) {
;     ...
;                 for (int s = 0; s < TC; ++s) {
;                     const LAS float* o = obase + (s + 1) * 320;
;                     const f32x4 now = *(const LAS f32x4*)(o), noa = *(const LAS f32x4*)(o + 4), nob = *(const LAS f32x4*)(o + 8), nok = *(const LAS f32x4*)(o + 12), norr = *(const LAS f32x4*)(o + 16);
;                     const f32x2 nvv = *(const LAS f32x2*)(vbase + (s + 1) * 64);
;                     const f32x2 p = pkfma_b<1>(C3, HI2(oa), pkfma_b<0>(C2, HI2(oa), pkfma_b<1>(C1, LO2(oa), pkmul_b<0>(C0, LO2(oa)))));
;                     float sa0 = p.x, sa1 = p.y;
;                     sa0 = reduce16(sa0); asm volatile("" : "+v"(sa0)); sa1 = reduce16(sa1);
;                     const f32x2 sap = {sa0, sa1};
;                     C0 = pkfma_b<0>(vv, LO2(ok), pkfma_b<0>(sap, LO2(ob), pkmul_b<0>(C0, LO2(ow))));
;                     C1 = pkfma_b<1>(vv, LO2(ok), pkfma_b<1>(sap, LO2(ob), pkmul_b<1>(C1, LO2(ow))));
;                     C2 = pkfma_b<0>(vv, HI2(ok), pkfma_b<0>(sap, HI2(ob), pkmul_b<0>(C2, HI2(ow))));
;                     C3 = pkfma_b<1>(vv, HI2(ok), pkfma_b<1>(sap, HI2(ob), pkmul_b<1>(C3, HI2(ow))));
;                     const f32x2 q = pkfma_b<1>(C3, HI2(orr), pkfma_b<0>(C2, HI2(orr), pkfma_b<1>(C1, LO2(orr), pkmul_b<0>(C0, LO2(orr)))));
;                     float y0 = q.x, y1 = q.y;
;                     y0 += dppf<0xB1>(y0); y1 += dppf<0xB1>(y1);
;                     *(LAS f32x2*)(yb + ((s * 32 + (r0 >> 1)) * 8 + ((lane >> 1) & 7)) * 2) = (f32x2){y0, y1};
;                     ow = now; oa = noa; ob = nob; ok = nok; orr = norr; vv = nvv;
;                 }
;             }
;             __syncthreads();
	v_pk_mul_f32 v[172:173], v[236:237], v[132:133] op_sel_hi:[1,0]
	v_pk_mul_f32 v[174:175], v[238:239], v[132:133] op_sel:[0,1]
	v_pk_fma_f32 v[172:173], v[240:241], v[134:135], v[172:173] op_sel_hi:[1,0,1]
	v_pk_fma_f32 v[174:175], v[242:243], v[134:135], v[174:175] op_sel:[0,1,0]
	v_pk_fma_f32 v[172:173], v[244:245], v[136:137], v[172:173] op_sel_hi:[1,0,1]
	v_pk_fma_f32 v[174:175], v[246:247], v[136:137], v[174:175] op_sel:[0,1,0]
	v_pk_fma_f32 v[172:173], v[248:249], v[138:139], v[172:173] op_sel_hi:[1,0,1]
	v_pk_fma_f32 v[174:175], v[250:251], v[138:139], v[174:175] op_sel:[0,1,0]
	ds_read_b128 v[132:135], v252 offset:19264
	ds_read_b128 v[136:139], v252 offset:19344
	v_pk_add_f32 v[172:173], v[172:173], v[174:175]
	ds_write_b64 v254, v[172:173] offset:28672
	s_waitcnt lgkmcnt(10)
	v_pk_mul_f32 v[168:169], v[236:237], v[100:101] op_sel_hi:[1,0]
	v_pk_mul_f32 v[170:171], v[238:239], v[100:101] op_sel:[0,1]
	v_pk_fma_f32 v[168:169], v[240:241], v[102:103], v[168:169] op_sel_hi:[1,0,1]
	v_pk_fma_f32 v[170:171], v[242:243], v[102:103], v[170:171] op_sel:[0,1,0]
	v_pk_fma_f32 v[168:169], v[244:245], v[104:105], v[168:169] op_sel_hi:[1,0,1]
	v_pk_fma_f32 v[170:171], v[246:247], v[104:105], v[170:171] op_sel:[0,1,0]
	v_pk_fma_f32 v[168:169], v[248:249], v[106:107], v[168:169] op_sel_hi:[1,0,1]
	v_pk_fma_f32 v[170:171], v[250:251], v[106:107], v[170:171] op_sel:[0,1,0]
	ds_read_b128 v[100:103], v176 offset:16
	ds_read_b128 v[104:107], v176 offset:96
	v_pk_add_f32 v[168:169], v[168:169], v[170:171]
	s_waitcnt lgkmcnt(10)
	v_pk_mul_f32 v[236:237], v[236:237], v[108:109] op_sel_hi:[1,0]
	v_pk_mul_f32 v[238:239], v[238:239], v[108:109] op_sel:[0,1]
	v_pk_mul_f32 v[240:241], v[240:241], v[110:111] op_sel_hi:[1,0]
	v_pk_mul_f32 v[242:243], v[242:243], v[110:111] op_sel:[0,1]
	v_pk_mul_f32 v[244:245], v[244:245], v[112:113] op_sel_hi:[1,0]
	v_pk_mul_f32 v[246:247], v[246:247], v[112:113] op_sel:[0,1]
	v_pk_mul_f32 v[248:249], v[248:249], v[114:115] op_sel_hi:[1,0]
	v_pk_mul_f32 v[250:251], v[250:251], v[114:115] op_sel:[0,1]
	v_add_f32_dpp v168, v168, v168 quad_perm:[1,0,3,2] row_mask:0xf bank_mask:0xf bound_ctrl:1
	v_add_f32_dpp v169, v169, v169 quad_perm:[1,0,3,2] row_mask:0xf bank_mask:0xf bound_ctrl:1
	ds_read_b128 v[108:111], v176
	v_add_f32_dpp v168, v168, v168 quad_perm:[2,3,0,1] row_mask:0xf bank_mask:0xf bound_ctrl:1
	v_add_f32_dpp v169, v169, v169 quad_perm:[2,3,0,1] row_mask:0xf bank_mask:0xf bound_ctrl:1
	ds_read_b128 v[112:115], v176 offset:80
	v_add_f32_dpp v168, v168, v168 row_half_mirror row_mask:0xf bank_mask:0xf bound_ctrl:1
	v_add_f32_dpp v169, v169, v169 row_half_mirror row_mask:0xf bank_mask:0xf bound_ctrl:1
	s_waitcnt lgkmcnt(10)
	v_pk_fma_f32 v[236:237], v[168:169], v[116:117], v[236:237] op_sel_hi:[1,0,1]
	v_pk_fma_f32 v[238:239], v[168:169], v[116:117], v[238:239] op_sel:[0,1,0]
	v_pk_fma_f32 v[240:241], v[168:169], v[118:119], v[240:241] op_sel_hi:[1,0,1]
	v_pk_fma_f32 v[242:243], v[168:169], v[118:119], v[242:243] op_sel:[0,1,0]
	v_pk_fma_f32 v[244:245], v[168:169], v[120:121], v[244:245] op_sel_hi:[1,0,1]
	v_pk_fma_f32 v[246:247], v[168:169], v[120:121], v[246:247] op_sel:[0,1,0]
	v_pk_fma_f32 v[248:249], v[168:169], v[122:123], v[248:249] op_sel_hi:[1,0,1]
	v_pk_fma_f32 v[250:251], v[168:169], v[122:123], v[250:251] op_sel:[0,1,0]
	ds_read_b128 v[116:119], v176 offset:32
	ds_read_b128 v[120:123], v176 offset:112
	s_waitcnt lgkmcnt(9)
	v_pk_fma_f32 v[236:237], v[166:167], v[124:125], v[236:237] op_sel_hi:[1,0,1]
	v_pk_fma_f32 v[238:239], v[166:167], v[124:125], v[238:239] op_sel:[0,1,0]
	v_pk_fma_f32 v[240:241], v[166:167], v[126:127], v[240:241] op_sel_hi:[1,0,1]
	v_pk_fma_f32 v[242:243], v[166:167], v[126:127], v[242:243] op_sel:[0,1,0]
	v_pk_fma_f32 v[244:245], v[166:167], v[128:129], v[244:245] op_sel_hi:[1,0,1]
	v_pk_fma_f32 v[246:247], v[166:167], v[128:129], v[246:247] op_sel:[0,1,0]
	v_pk_fma_f32 v[248:249], v[166:167], v[130:131], v[248:249] op_sel_hi:[1,0,1]
	v_pk_fma_f32 v[250:251], v[166:167], v[130:131], v[250:251] op_sel:[0,1,0]
	ds_read_b128 v[124:127], v176 offset:48
	ds_read_b128 v[128:131], v176 offset:128
	ds_read_b64 v[166:167], v177
	s_waitcnt lgkmcnt(10)
	v_pk_mul_f32 v[172:173], v[236:237], v[132:133] op_sel_hi:[1,0]
	v_pk_mul_f32 v[174:175], v[238:239], v[132:133] op_sel:[0,1]
	v_pk_fma_f32 v[172:173], v[240:241], v[134:135], v[172:173] op_sel_hi:[1,0,1]
	v_pk_fma_f32 v[174:175], v[242:243], v[134:135], v[174:175] op_sel:[0,1,0]
	v_pk_fma_f32 v[172:173], v[244:245], v[136:137], v[172:173] op_sel_hi:[1,0,1]
	v_pk_fma_f32 v[174:175], v[246:247], v[136:137], v[174:175] op_sel:[0,1,0]
	v_pk_fma_f32 v[172:173], v[248:249], v[138:139], v[172:173] op_sel_hi:[1,0,1]
	v_pk_fma_f32 v[174:175], v[250:251], v[138:139], v[174:175] op_sel:[0,1,0]
	ds_read_b128 v[132:135], v176 offset:64
	ds_read_b128 v[136:139], v176 offset:144
	v_pk_add_f32 v[172:173], v[172:173], v[174:175]
	ds_write_b64 v254, v[172:173] offset:30720
	v_add_u32_e32 v252, s42, v252
	v_add_u32_e32 v253, s43, v253
	v_add_u32_e32 v254, s44, v254
	v_subrev_u32_e32 v176, s42, v176
	v_subrev_u32_e32 v177, s43, v177
	s_sub_i32 s42, 0, s42
	s_sub_i32 s43, 0, s43
	s_sub_i32 s44, 0, s44
	s_add_i32 s23, s23, 1
	s_cmpk_lg_u32 s23, 0x100
	s_waitcnt lgkmcnt(0)
	s_barrier
	s_cbranch_scc1 .LW_rloop
	s_setprio 0
	s_branch .LBB0_2062
